# GEMM segment edges re-cut for the new MFMA order: trailing s_barrier directly after the last MFMA (before s_setprio 0), s_setprio 1 ahead of the pre-MFMA barrier
# speedup vs baseline: 1.0373x; 1.0071x over previous
.LBB0_95:
	s_add_u32 s16, s14, 0xfff80080
	s_addc_u32 s17, s15, -1
	s_add_i32 s42, 0, 0x10000
	v_add_u32_e32 v145, s42, v142
	ds_read_b128 v[146:149], v145
	ds_read_b128 v[150:153], v145 offset:1024
	ds_read_b128 v[154:157], v145 offset:2048
	ds_read_b128 v[158:161], v145 offset:3072
	s_cmp_eq_u32 s41, 28
	s_cselect_b32 s19, s9, s17
	s_cselect_b32 s18, s37, s16
	s_cselect_b32 s17, s7, s40
	s_cselect_b32 s16, s38, s39
	s_add_i32 m0, s27, 0xc000
	ds_read_b128 v[162:165], v144
	ds_read_b128 v[166:169], v144 offset:1024
	ds_read_b128 v[170:173], v144 offset:2048
	ds_read_b128 v[174:177], v144 offset:3072
	ds_read_b128 v[178:181], v144 offset:4096
	ds_read_b128 v[182:185], v144 offset:5120
	ds_read_b128 v[186:189], v144 offset:6144
	ds_read_b128 v[190:193], v144 offset:7168
	global_load_lds_dwordx4 v138, s[14:15]
	s_add_i32 m0, s27, 0xe000
	s_nop 0
	global_load_lds_dwordx4 v140, s[14:15]
	s_waitcnt lgkmcnt(8)
	s_setprio 1
	s_barrier
	s_waitcnt lgkmcnt(0)
	v_mfma_f32_16x16x32_bf16 v[128:131], v[146:149], v[162:165], v[128:131]
	v_mfma_f32_16x16x32_bf16 v[128:131], v[150:153], v[166:169], v[128:131]
	v_mfma_f32_16x16x32_bf16 v[120:123], v[150:153], v[174:177], v[120:123]
	v_mfma_f32_16x16x32_bf16 v[120:123], v[146:149], v[170:173], v[120:123]
	v_mfma_f32_16x16x32_bf16 v[104:107], v[146:149], v[178:181], v[104:107]
	v_mfma_f32_16x16x32_bf16 v[104:107], v[150:153], v[182:185], v[104:107]
	v_mfma_f32_16x16x32_bf16 v[88:91], v[150:153], v[190:193], v[88:91]
	v_mfma_f32_16x16x32_bf16 v[88:91], v[146:149], v[186:189], v[88:91]
	v_mfma_f32_16x16x32_bf16 v[84:87], v[154:157], v[186:189], v[84:87]
	v_mfma_f32_16x16x32_bf16 v[84:87], v[158:161], v[190:193], v[84:87]
	v_mfma_f32_16x16x32_bf16 v[100:103], v[158:161], v[182:185], v[100:103]
	v_mfma_f32_16x16x32_bf16 v[100:103], v[154:157], v[178:181], v[100:103]
	v_mfma_f32_16x16x32_bf16 v[116:119], v[154:157], v[170:173], v[116:119]
	v_mfma_f32_16x16x32_bf16 v[116:119], v[158:161], v[174:177], v[116:119]
	v_mfma_f32_16x16x32_bf16 v[124:127], v[158:161], v[166:169], v[124:127]
	v_mfma_f32_16x16x32_bf16 v[124:127], v[154:157], v[162:165], v[124:127]
	s_barrier
	s_setprio 0
	s_add_i32 s44, 0, 0x14000
	s_add_i32 s42, s42, s26
	v_add_u32_e32 v145, s44, v142
	v_lshl_add_u64 v[212:213], s[16:17], 0, v[2:3]
	s_mov_b32 m0, s42
	ds_read_b128 v[194:197], v145
	ds_read_b128 v[200:203], v145 offset:1024
	ds_read_b128 v[204:207], v145 offset:2048
	ds_read_b128 v[208:211], v145 offset:3072
	global_load_lds_dwordx4 v[212:213], off
	v_lshl_add_u64 v[214:215], s[16:17], 0, v[132:133]
	s_add_i32 m0, s42, 0x2000
	s_nop 0
	global_load_lds_dwordx4 v[214:215], off
	s_setprio 1
	s_barrier
	s_waitcnt lgkmcnt(0)
	v_mfma_f32_16x16x32_bf16 v[112:115], v[194:197], v[162:165], v[112:115]
	v_mfma_f32_16x16x32_bf16 v[112:115], v[200:203], v[166:169], v[112:115]
	v_mfma_f32_16x16x32_bf16 v[96:99], v[200:203], v[174:177], v[96:99]
	v_mfma_f32_16x16x32_bf16 v[96:99], v[194:197], v[170:173], v[96:99]
	v_mfma_f32_16x16x32_bf16 v[80:83], v[194:197], v[178:181], v[80:83]
	v_mfma_f32_16x16x32_bf16 v[80:83], v[200:203], v[182:185], v[80:83]
	v_mfma_f32_16x16x32_bf16 v[72:75], v[200:203], v[190:193], v[72:75]
	v_mfma_f32_16x16x32_bf16 v[72:75], v[194:197], v[186:189], v[72:75]
	v_mfma_f32_16x16x32_bf16 v[68:71], v[204:207], v[186:189], v[68:71]
	v_mfma_f32_16x16x32_bf16 v[68:71], v[208:211], v[190:193], v[68:71]
	v_mfma_f32_16x16x32_bf16 v[76:79], v[208:211], v[182:185], v[76:79]
	v_mfma_f32_16x16x32_bf16 v[76:79], v[204:207], v[178:181], v[76:79]
	v_mfma_f32_16x16x32_bf16 v[92:95], v[204:207], v[170:173], v[92:95]
	v_mfma_f32_16x16x32_bf16 v[92:95], v[208:211], v[174:177], v[92:95]
	v_mfma_f32_16x16x32_bf16 v[108:111], v[208:211], v[166:169], v[108:111]
	v_mfma_f32_16x16x32_bf16 v[108:111], v[204:207], v[162:165], v[108:111]
	s_barrier
	s_setprio 0
	s_mov_b32 m0, s27
	v_lshl_add_u64 v[216:217], s[18:19], 0, v[136:137]
	ds_read_b128 v[162:165], v144 offset:16384
	ds_read_b128 v[166:169], v144 offset:17408
	ds_read_b128 v[170:173], v144 offset:18432
	ds_read_b128 v[174:177], v144 offset:19456
	ds_read_b128 v[178:181], v144 offset:20480
	ds_read_b128 v[182:185], v144 offset:21504
	ds_read_b128 v[186:189], v144 offset:22528
	ds_read_b128 v[190:193], v144 offset:23552
	global_load_lds_dwordx4 v[216:217], off
	v_lshl_add_u64 v[218:219], s[18:19], 0, v[134:135]
	s_mov_b32 m0, s28
	s_nop 0
	global_load_lds_dwordx4 v[218:219], off
	s_waitcnt vmcnt(10)
	s_setprio 1
	s_barrier
	s_waitcnt lgkmcnt(0)
	v_mfma_f32_16x16x32_bf16 v[64:67], v[146:149], v[162:165], v[64:67]
	v_mfma_f32_16x16x32_bf16 v[64:67], v[150:153], v[166:169], v[64:67]
	v_mfma_f32_16x16x32_bf16 v[56:59], v[150:153], v[174:177], v[56:59]
	v_mfma_f32_16x16x32_bf16 v[56:59], v[146:149], v[170:173], v[56:59]
	v_mfma_f32_16x16x32_bf16 v[40:43], v[146:149], v[178:181], v[40:43]
	v_mfma_f32_16x16x32_bf16 v[40:43], v[150:153], v[182:185], v[40:43]
	v_mfma_f32_16x16x32_bf16 v[24:27], v[150:153], v[190:193], v[24:27]
	v_mfma_f32_16x16x32_bf16 v[24:27], v[146:149], v[186:189], v[24:27]
	v_mfma_f32_16x16x32_bf16 v[20:23], v[154:157], v[186:189], v[20:23]
	v_mfma_f32_16x16x32_bf16 v[20:23], v[158:161], v[190:193], v[20:23]
	v_mfma_f32_16x16x32_bf16 v[36:39], v[158:161], v[182:185], v[36:39]
	v_mfma_f32_16x16x32_bf16 v[36:39], v[154:157], v[178:181], v[36:39]
	v_mfma_f32_16x16x32_bf16 v[52:55], v[154:157], v[170:173], v[52:55]
	v_mfma_f32_16x16x32_bf16 v[52:55], v[158:161], v[174:177], v[52:55]
	v_mfma_f32_16x16x32_bf16 v[60:63], v[158:161], v[166:169], v[60:63]
	v_mfma_f32_16x16x32_bf16 v[60:63], v[154:157], v[162:165], v[60:63]
	s_barrier
	s_setprio 0
	s_add_u32 s42, s16, 0x20000
	s_addc_u32 s43, s17, 0
	s_add_i32 s44, s44, s26
	s_mov_b32 m0, s44
	s_nop 0
	global_load_lds_dwordx4 v2, s[42:43]
	s_add_i32 m0, s44, 0x2000
	s_nop 0
	global_load_lds_dwordx4 v132, s[42:43]
	s_add_i32 s42, 0, 0x18000
	v_add_u32_e32 v145, s42, v142
	ds_read_b128 v[146:149], v145
	ds_read_b128 v[150:153], v145 offset:1024
	ds_read_b128 v[154:157], v145 offset:2048
	ds_read_b128 v[158:161], v145 offset:3072
	s_waitcnt vmcnt(6)
	s_setprio 1
	s_barrier
	v_mfma_f32_16x16x32_bf16 v[48:51], v[194:197], v[162:165], v[48:51]
	v_mfma_f32_16x16x32_bf16 v[48:51], v[200:203], v[166:169], v[48:51]
	v_mfma_f32_16x16x32_bf16 v[32:35], v[200:203], v[174:177], v[32:35]
	v_mfma_f32_16x16x32_bf16 v[32:35], v[194:197], v[170:173], v[32:35]
	v_mfma_f32_16x16x32_bf16 v[16:19], v[194:197], v[178:181], v[16:19]
	v_mfma_f32_16x16x32_bf16 v[16:19], v[200:203], v[182:185], v[16:19]
	v_mfma_f32_16x16x32_bf16 v[8:11], v[200:203], v[190:193], v[8:11]
	v_mfma_f32_16x16x32_bf16 v[8:11], v[194:197], v[186:189], v[8:11]
	v_mfma_f32_16x16x32_bf16 v[4:7], v[204:207], v[186:189], v[4:7]
	v_mfma_f32_16x16x32_bf16 v[4:7], v[208:211], v[190:193], v[4:7]
	v_mfma_f32_16x16x32_bf16 v[12:15], v[208:211], v[182:185], v[12:15]
	v_mfma_f32_16x16x32_bf16 v[12:15], v[204:207], v[178:181], v[12:15]
	v_mfma_f32_16x16x32_bf16 v[28:31], v[204:207], v[170:173], v[28:31]
	v_mfma_f32_16x16x32_bf16 v[28:31], v[208:211], v[174:177], v[28:31]
	v_mfma_f32_16x16x32_bf16 v[44:47], v[208:211], v[166:169], v[44:47]
	v_mfma_f32_16x16x32_bf16 v[44:47], v[204:207], v[162:165], v[44:47]
	s_barrier
	s_setprio 0
	s_add_u32 s18, s18, 0x80000
	s_addc_u32 s19, s19, 0
	s_mov_b32 m0, s29
	ds_read_b128 v[162:165], v144 offset:32768
	ds_read_b128 v[166:169], v144 offset:33792
	ds_read_b128 v[170:173], v144 offset:34816
	ds_read_b128 v[174:177], v144 offset:35840
	ds_read_b128 v[178:181], v144 offset:36864
	ds_read_b128 v[182:185], v144 offset:37888
	ds_read_b128 v[186:189], v144 offset:38912
	ds_read_b128 v[190:193], v144 offset:39936
	global_load_lds_dwordx4 v136, s[18:19]
	s_mov_b32 m0, s30
	s_nop 0
	global_load_lds_dwordx4 v134, s[18:19]
	s_waitcnt lgkmcnt(8)
	s_setprio 1
	s_barrier
	s_waitcnt lgkmcnt(0)
	v_mfma_f32_16x16x32_bf16 v[128:131], v[146:149], v[162:165], v[128:131]
	v_mfma_f32_16x16x32_bf16 v[128:131], v[150:153], v[166:169], v[128:131]
	v_mfma_f32_16x16x32_bf16 v[120:123], v[150:153], v[174:177], v[120:123]
	v_mfma_f32_16x16x32_bf16 v[120:123], v[146:149], v[170:173], v[120:123]
	v_mfma_f32_16x16x32_bf16 v[104:107], v[146:149], v[178:181], v[104:107]
	v_mfma_f32_16x16x32_bf16 v[104:107], v[150:153], v[182:185], v[104:107]
	v_mfma_f32_16x16x32_bf16 v[88:91], v[150:153], v[190:193], v[88:91]
	v_mfma_f32_16x16x32_bf16 v[88:91], v[146:149], v[186:189], v[88:91]
	v_mfma_f32_16x16x32_bf16 v[84:87], v[154:157], v[186:189], v[84:87]
	v_mfma_f32_16x16x32_bf16 v[84:87], v[158:161], v[190:193], v[84:87]
	v_mfma_f32_16x16x32_bf16 v[100:103], v[158:161], v[182:185], v[100:103]
	v_mfma_f32_16x16x32_bf16 v[100:103], v[154:157], v[178:181], v[100:103]
	v_mfma_f32_16x16x32_bf16 v[116:119], v[154:157], v[170:173], v[116:119]
	v_mfma_f32_16x16x32_bf16 v[116:119], v[158:161], v[174:177], v[116:119]
	v_mfma_f32_16x16x32_bf16 v[124:127], v[158:161], v[166:169], v[124:127]
	v_mfma_f32_16x16x32_bf16 v[124:127], v[154:157], v[162:165], v[124:127]
	s_barrier
	s_setprio 0
	s_add_i32 s18, 0, 0x1c000
	s_add_i32 s19, s42, s26
	v_add_u32_e32 v145, s18, v142
	v_lshl_add_u64 v[212:213], v[212:213], 0, s[2:3]
	s_mov_b32 m0, s19
	ds_read_b128 v[194:197], v145
	ds_read_b128 v[200:203], v145 offset:1024
	ds_read_b128 v[204:207], v145 offset:2048
	ds_read_b128 v[208:211], v145 offset:3072
	global_load_lds_dwordx4 v[212:213], off
	v_lshl_add_u64 v[212:213], v[214:215], 0, s[2:3]
	s_add_i32 m0, s19, 0x2000
	s_nop 0
	global_load_lds_dwordx4 v[212:213], off
	s_setprio 1
	s_barrier
	s_waitcnt lgkmcnt(0)
	v_mfma_f32_16x16x32_bf16 v[112:115], v[194:197], v[162:165], v[112:115]
	v_mfma_f32_16x16x32_bf16 v[112:115], v[200:203], v[166:169], v[112:115]
	v_mfma_f32_16x16x32_bf16 v[96:99], v[200:203], v[174:177], v[96:99]
	v_mfma_f32_16x16x32_bf16 v[96:99], v[194:197], v[170:173], v[96:99]
	v_mfma_f32_16x16x32_bf16 v[80:83], v[194:197], v[178:181], v[80:83]
	v_mfma_f32_16x16x32_bf16 v[80:83], v[200:203], v[182:185], v[80:83]
	v_mfma_f32_16x16x32_bf16 v[72:75], v[200:203], v[190:193], v[72:75]
	v_mfma_f32_16x16x32_bf16 v[72:75], v[194:197], v[186:189], v[72:75]
	v_mfma_f32_16x16x32_bf16 v[68:71], v[204:207], v[186:189], v[68:71]
	v_mfma_f32_16x16x32_bf16 v[68:71], v[208:211], v[190:193], v[68:71]
	v_mfma_f32_16x16x32_bf16 v[76:79], v[208:211], v[182:185], v[76:79]
	v_mfma_f32_16x16x32_bf16 v[76:79], v[204:207], v[178:181], v[76:79]
	v_mfma_f32_16x16x32_bf16 v[92:95], v[204:207], v[170:173], v[92:95]
	v_mfma_f32_16x16x32_bf16 v[92:95], v[208:211], v[174:177], v[92:95]
	v_mfma_f32_16x16x32_bf16 v[108:111], v[208:211], v[166:169], v[108:111]
	v_mfma_f32_16x16x32_bf16 v[108:111], v[204:207], v[162:165], v[108:111]
	s_barrier
	s_setprio 0
	s_mov_b32 m0, s31
	v_lshl_add_u64 v[212:213], v[216:217], 0, s[2:3]
	ds_read_b128 v[162:165], v144 offset:49152
	ds_read_b128 v[166:169], v144 offset:50176
	ds_read_b128 v[170:173], v144 offset:51200
	ds_read_b128 v[174:177], v144 offset:52224
	ds_read_b128 v[178:181], v144 offset:53248
	ds_read_b128 v[182:185], v144 offset:54272
	ds_read_b128 v[186:189], v144 offset:55296
	ds_read_b128 v[190:193], v144 offset:56320
	global_load_lds_dwordx4 v[212:213], off
	v_lshl_add_u64 v[212:213], v[218:219], 0, s[2:3]
	s_mov_b32 m0, s33
	s_nop 0
	global_load_lds_dwordx4 v[212:213], off
	s_setprio 1
	s_barrier
	s_waitcnt lgkmcnt(0)
	v_mfma_f32_16x16x32_bf16 v[64:67], v[146:149], v[162:165], v[64:67]
	v_mfma_f32_16x16x32_bf16 v[64:67], v[150:153], v[166:169], v[64:67]
	v_mfma_f32_16x16x32_bf16 v[56:59], v[150:153], v[174:177], v[56:59]
	v_mfma_f32_16x16x32_bf16 v[56:59], v[146:149], v[170:173], v[56:59]
	v_mfma_f32_16x16x32_bf16 v[40:43], v[146:149], v[178:181], v[40:43]
	v_mfma_f32_16x16x32_bf16 v[40:43], v[150:153], v[182:185], v[40:43]
	v_mfma_f32_16x16x32_bf16 v[24:27], v[150:153], v[190:193], v[24:27]
	v_mfma_f32_16x16x32_bf16 v[24:27], v[146:149], v[186:189], v[24:27]
	v_mfma_f32_16x16x32_bf16 v[20:23], v[154:157], v[186:189], v[20:23]
	v_mfma_f32_16x16x32_bf16 v[20:23], v[158:161], v[190:193], v[20:23]
	v_mfma_f32_16x16x32_bf16 v[36:39], v[158:161], v[182:185], v[36:39]
	v_mfma_f32_16x16x32_bf16 v[36:39], v[154:157], v[178:181], v[36:39]
	v_mfma_f32_16x16x32_bf16 v[52:55], v[154:157], v[170:173], v[52:55]
	v_mfma_f32_16x16x32_bf16 v[52:55], v[158:161], v[174:177], v[52:55]
	v_mfma_f32_16x16x32_bf16 v[60:63], v[158:161], v[166:169], v[60:63]
	v_mfma_f32_16x16x32_bf16 v[60:63], v[154:157], v[162:165], v[60:63]
	s_barrier
	s_setprio 0
	s_add_u32 s16, s16, 0x20080
	s_addc_u32 s17, s17, 0
	s_add_i32 s18, s18, s26
	s_mov_b32 m0, s18
	s_nop 0
	global_load_lds_dwordx4 v2, s[16:17]
	s_add_i32 m0, s18, 0x2000
	s_nop 0
	global_load_lds_dwordx4 v132, s[16:17]
	s_waitcnt vmcnt(6)
	s_setprio 1
	s_barrier
	v_mfma_f32_16x16x32_bf16 v[48:51], v[194:197], v[162:165], v[48:51]
	v_mfma_f32_16x16x32_bf16 v[48:51], v[200:203], v[166:169], v[48:51]
	v_mfma_f32_16x16x32_bf16 v[32:35], v[200:203], v[174:177], v[32:35]
	v_mfma_f32_16x16x32_bf16 v[32:35], v[194:197], v[170:173], v[32:35]
	v_mfma_f32_16x16x32_bf16 v[16:19], v[194:197], v[178:181], v[16:19]
	v_mfma_f32_16x16x32_bf16 v[16:19], v[200:203], v[182:185], v[16:19]
	v_mfma_f32_16x16x32_bf16 v[8:11], v[200:203], v[190:193], v[8:11]
	v_mfma_f32_16x16x32_bf16 v[8:11], v[194:197], v[186:189], v[8:11]
	v_mfma_f32_16x16x32_bf16 v[4:7], v[204:207], v[186:189], v[4:7]
	v_mfma_f32_16x16x32_bf16 v[4:7], v[208:211], v[190:193], v[4:7]
	v_mfma_f32_16x16x32_bf16 v[12:15], v[208:211], v[182:185], v[12:15]
	v_mfma_f32_16x16x32_bf16 v[12:15], v[204:207], v[178:181], v[12:15]
	v_mfma_f32_16x16x32_bf16 v[28:31], v[204:207], v[170:173], v[28:31]
	v_mfma_f32_16x16x32_bf16 v[28:31], v[208:211], v[174:177], v[28:31]
	v_mfma_f32_16x16x32_bf16 v[44:47], v[208:211], v[166:169], v[44:47]
	v_mfma_f32_16x16x32_bf16 v[44:47], v[204:207], v[162:165], v[44:47]
	s_barrier
	s_setprio 0
	s_add_i32 s41, s41, 2
	s_add_u32 s14, s14, 0x100
	s_addc_u32 s15, s15, 0
	s_add_u32 s39, s39, 0x100
	s_addc_u32 s40, s40, 0
	s_cmp_gt_u32 s41, 29
	s_cbranch_scc0 .LBB0_95
	v_lshl_add_u32 v145, s36, 8, v1
	v_lshl_or_b32 v146, s35, 8, v143
	v_ashrrev_i32_e32 v147, 31, v146
	v_mov_b64_e32 v[148:149], s[4:5]
	s_mov_b32 s7, 0x8200
	v_cvt_pk_bf16_f32 v72, v72, v73
	v_cvt_pk_bf16_f32 v73, v74, v75
	v_cvt_pk_bf16_f32 v74, v68, v69
	v_add_u32_e32 v68, 0x80, v145
	v_mad_i64_i32 v[150:151], s[14:15], v145, s7, v[148:149]
	v_lshlrev_b64 v[146:147], 1, v[146:147]
	v_cvt_pk_bf16_f32 v112, v112, v113
	v_cvt_pk_bf16_f32 v113, v114, v115
	v_cvt_pk_bf16_f32 v114, v108, v109
	v_or_b32_e32 v108, 16, v145
	v_mad_i64_i32 v[68:69], s[14:15], v68, s7, v[148:149]
	v_cvt_pk_bf16_f32 v48, v48, v49
	v_cvt_pk_bf16_f32 v49, v50, v51
	v_cvt_pk_bf16_f32 v50, v44, v45
	v_add_u32_e32 v44, 0x90, v145
	v_lshl_add_u64 v[150:151], v[150:151], 0, v[146:147]
	v_cvt_pk_bf16_f32 v115, v110, v111
	v_mad_i64_i32 v[108:109], s[14:15], v108, s7, v[148:149]
	v_cvt_pk_bf16_f32 v96, v96, v97
	v_cvt_pk_bf16_f32 v97, v98, v99
	v_cvt_pk_bf16_f32 v98, v92, v93
	v_or_b32_e32 v92, 32, v145
	v_lshl_add_u64 v[68:69], v[68:69], 0, v[146:147]
	v_cvt_pk_bf16_f32 v51, v46, v47
	v_mad_i64_i32 v[44:45], s[14:15], v44, s7, v[148:149]
	v_cvt_pk_bf16_f32 v32, v32, v33
	v_cvt_pk_bf16_f32 v33, v34, v35
	v_cvt_pk_bf16_f32 v34, v28, v29
	v_add_u32_e32 v28, 0xa0, v145
	global_store_dwordx4 v[150:151], v[112:115], off offset:64 nt
	v_cvt_pk_bf16_f32 v99, v94, v95
	v_mad_i64_i32 v[92:93], s[14:15], v92, s7, v[148:149]
	v_lshl_add_u64 v[112:113], v[108:109], 0, v[146:147]
	v_cvt_pk_bf16_f32 v80, v80, v81
	v_cvt_pk_bf16_f32 v81, v82, v83
	v_cvt_pk_bf16_f32 v82, v76, v77
	v_or_b32_e32 v76, 48, v145
	global_store_dwordx4 v[68:69], v[48:51], off offset:64 nt
	v_cvt_pk_bf16_f32 v35, v30, v31
	v_mad_i64_i32 v[28:29], s[14:15], v28, s7, v[148:149]
	v_lshl_add_u64 v[48:49], v[44:45], 0, v[146:147]
	v_cvt_pk_bf16_f32 v16, v16, v17
	v_cvt_pk_bf16_f32 v17, v18, v19
	v_cvt_pk_bf16_f32 v18, v12, v13
	v_add_u32_e32 v12, 0xb0, v145
	global_store_dwordx4 v[112:113], v[96:99], off offset:64 nt
	v_cvt_pk_bf16_f32 v83, v78, v79
	v_mad_i64_i32 v[76:77], s[14:15], v76, s7, v[148:149]
	v_lshl_add_u64 v[96:97], v[92:93], 0, v[146:147]
	global_store_dwordx4 v[48:49], v[32:35], off offset:64 nt
	v_cvt_pk_bf16_f32 v19, v14, v15
	v_mad_i64_i32 v[12:13], s[14:15], v12, s7, v[148:149]
	v_lshl_add_u64 v[32:33], v[28:29], 0, v[146:147]
	v_cvt_pk_bf16_f32 v128, v128, v129
	v_cvt_pk_bf16_f32 v129, v130, v131
	v_cvt_pk_bf16_f32 v130, v124, v125
	v_cvt_pk_bf16_f32 v131, v126, v127
	v_cvt_pk_bf16_f32 v108, v120, v121
	v_cvt_pk_bf16_f32 v109, v122, v123
	v_cvt_pk_bf16_f32 v110, v116, v117
	v_cvt_pk_bf16_f32 v111, v118, v119
	v_cvt_pk_bf16_f32 v92, v104, v105
	v_cvt_pk_bf16_f32 v93, v106, v107
	v_cvt_pk_bf16_f32 v94, v100, v101
	v_cvt_pk_bf16_f32 v95, v102, v103
	global_store_dwordx4 v[96:97], v[80:83], off offset:64 nt
	v_cvt_pk_bf16_f32 v78, v84, v85
	v_cvt_pk_bf16_f32 v79, v86, v87
	v_lshl_add_u64 v[80:81], v[76:77], 0, v[146:147]
	v_cvt_pk_bf16_f32 v76, v88, v89
	v_cvt_pk_bf16_f32 v77, v90, v91
	v_cvt_pk_bf16_f32 v75, v70, v71
	v_cvt_pk_bf16_f32 v64, v64, v65
	v_cvt_pk_bf16_f32 v65, v66, v67
	v_cvt_pk_bf16_f32 v66, v60, v61
	v_cvt_pk_bf16_f32 v67, v62, v63
	v_cvt_pk_bf16_f32 v44, v56, v57
	v_cvt_pk_bf16_f32 v45, v58, v59
	v_cvt_pk_bf16_f32 v46, v52, v53
	v_cvt_pk_bf16_f32 v47, v54, v55
	v_cvt_pk_bf16_f32 v28, v40, v41
	v_cvt_pk_bf16_f32 v29, v42, v43
	v_cvt_pk_bf16_f32 v30, v36, v37
	v_cvt_pk_bf16_f32 v31, v38, v39
	global_store_dwordx4 v[32:33], v[16:19], off offset:64 nt
	v_cvt_pk_bf16_f32 v14, v20, v21
	v_cvt_pk_bf16_f32 v15, v22, v23
	v_lshl_add_u64 v[16:17], v[12:13], 0, v[146:147]
	v_cvt_pk_bf16_f32 v12, v24, v25
	v_cvt_pk_bf16_f32 v13, v26, v27
	v_cvt_pk_bf16_f32 v8, v8, v9
	v_cvt_pk_bf16_f32 v9, v10, v11
	v_cvt_pk_bf16_f32 v10, v4, v5
	v_cvt_pk_bf16_f32 v11, v6, v7
	s_and_b64 vcc, exec, s[0:1]
	s_mov_b32 s35, s6
	s_mov_b32 s36, s8
	s_mov_b64 s[16:17], s[12:13]
	s_mov_b64 s[14:15], s[10:11]
	global_store_dwordx4 v[150:151], v[128:131], off nt
	global_store_dwordx4 v[112:113], v[108:111], off nt
	global_store_dwordx4 v[96:97], v[92:95], off nt
	global_store_dwordx4 v[80:81], v[76:79], off nt
	global_store_dwordx4 v[80:81], v[72:75], off offset:64 nt
	global_store_dwordx4 v[68:69], v[64:67], off nt
	global_store_dwordx4 v[48:49], v[44:47], off nt
	global_store_dwordx4 v[32:33], v[28:31], off nt
	global_store_dwordx4 v[16:17], v[12:15], off nt
	global_store_dwordx4 v[16:17], v[8:11], off offset:64 nt
	s_cbranch_vccz .LBB0_92
	s_waitcnt vmcnt(0)
	s_cmpk_gt_u32 s21, 0xff
	s_cbranch_scc1 .LBB0_99
	s_barrier

.LBB0_236:
	s_add_u32 s16, s14, 0xfffe0080
	s_addc_u32 s17, s15, -1
	s_add_i32 s41, 0, 0x10000
	v_add_u32_e32 v145, s41, v142
	ds_read_b128 v[146:149], v145
	ds_read_b128 v[150:153], v145 offset:1024
	ds_read_b128 v[154:157], v145 offset:2048
	ds_read_b128 v[158:161], v145 offset:3072
	s_cmp_eq_u32 s40, 4
	s_cselect_b32 s19, s9, s17
	s_cselect_b32 s18, s36, s16
	s_cselect_b32 s17, s7, s39
	s_cselect_b32 s16, s37, s38
	s_add_i32 m0, s26, 0xc000
	ds_read_b128 v[162:165], v144
	ds_read_b128 v[166:169], v144 offset:1024
	ds_read_b128 v[170:173], v144 offset:2048
	ds_read_b128 v[174:177], v144 offset:3072
	ds_read_b128 v[178:181], v144 offset:4096
	ds_read_b128 v[182:185], v144 offset:5120
	ds_read_b128 v[186:189], v144 offset:6144
	ds_read_b128 v[190:193], v144 offset:7168
	global_load_lds_dwordx4 v138, s[14:15]
	s_add_i32 m0, s26, 0xe000
	s_nop 0
	global_load_lds_dwordx4 v140, s[14:15]
	s_waitcnt lgkmcnt(8)
	s_setprio 1
	s_barrier
	s_waitcnt lgkmcnt(0)
	v_mfma_f32_16x16x32_bf16 v[128:131], v[146:149], v[162:165], v[128:131]
	v_mfma_f32_16x16x32_bf16 v[128:131], v[150:153], v[166:169], v[128:131]
	v_mfma_f32_16x16x32_bf16 v[120:123], v[150:153], v[174:177], v[120:123]
	v_mfma_f32_16x16x32_bf16 v[120:123], v[146:149], v[170:173], v[120:123]
	v_mfma_f32_16x16x32_bf16 v[104:107], v[146:149], v[178:181], v[104:107]
	v_mfma_f32_16x16x32_bf16 v[104:107], v[150:153], v[182:185], v[104:107]
	v_mfma_f32_16x16x32_bf16 v[88:91], v[150:153], v[190:193], v[88:91]
	v_mfma_f32_16x16x32_bf16 v[88:91], v[146:149], v[186:189], v[88:91]
	v_mfma_f32_16x16x32_bf16 v[84:87], v[154:157], v[186:189], v[84:87]
	v_mfma_f32_16x16x32_bf16 v[84:87], v[158:161], v[190:193], v[84:87]
	v_mfma_f32_16x16x32_bf16 v[100:103], v[158:161], v[182:185], v[100:103]
	v_mfma_f32_16x16x32_bf16 v[100:103], v[154:157], v[178:181], v[100:103]
	v_mfma_f32_16x16x32_bf16 v[116:119], v[154:157], v[170:173], v[116:119]
	v_mfma_f32_16x16x32_bf16 v[116:119], v[158:161], v[174:177], v[116:119]
	v_mfma_f32_16x16x32_bf16 v[124:127], v[158:161], v[166:169], v[124:127]
	v_mfma_f32_16x16x32_bf16 v[124:127], v[154:157], v[162:165], v[124:127]
	s_barrier
	s_setprio 0
	s_add_i32 s44, 0, 0x14000
	s_add_i32 s41, s41, s25
	v_add_u32_e32 v145, s44, v142
	v_lshl_add_u64 v[212:213], s[16:17], 0, v[2:3]
	s_mov_b32 m0, s41
	ds_read_b128 v[194:197], v145
	ds_read_b128 v[200:203], v145 offset:1024
	ds_read_b128 v[204:207], v145 offset:2048
	ds_read_b128 v[208:211], v145 offset:3072
	global_load_lds_dwordx4 v[212:213], off
	v_lshl_add_u64 v[214:215], s[16:17], 0, v[132:133]
	s_add_i32 m0, s41, 0x2000
	s_nop 0
	global_load_lds_dwordx4 v[214:215], off
	s_setprio 1
	s_barrier
	s_waitcnt lgkmcnt(0)
	v_mfma_f32_16x16x32_bf16 v[112:115], v[194:197], v[162:165], v[112:115]
	v_mfma_f32_16x16x32_bf16 v[112:115], v[200:203], v[166:169], v[112:115]
	v_mfma_f32_16x16x32_bf16 v[96:99], v[200:203], v[174:177], v[96:99]
	v_mfma_f32_16x16x32_bf16 v[96:99], v[194:197], v[170:173], v[96:99]
	v_mfma_f32_16x16x32_bf16 v[80:83], v[194:197], v[178:181], v[80:83]
	v_mfma_f32_16x16x32_bf16 v[80:83], v[200:203], v[182:185], v[80:83]
	v_mfma_f32_16x16x32_bf16 v[72:75], v[200:203], v[190:193], v[72:75]
	v_mfma_f32_16x16x32_bf16 v[72:75], v[194:197], v[186:189], v[72:75]
	v_mfma_f32_16x16x32_bf16 v[68:71], v[204:207], v[186:189], v[68:71]
	v_mfma_f32_16x16x32_bf16 v[68:71], v[208:211], v[190:193], v[68:71]
	v_mfma_f32_16x16x32_bf16 v[76:79], v[208:211], v[182:185], v[76:79]
	v_mfma_f32_16x16x32_bf16 v[76:79], v[204:207], v[178:181], v[76:79]
	v_mfma_f32_16x16x32_bf16 v[92:95], v[204:207], v[170:173], v[92:95]
	v_mfma_f32_16x16x32_bf16 v[92:95], v[208:211], v[174:177], v[92:95]
	v_mfma_f32_16x16x32_bf16 v[108:111], v[208:211], v[166:169], v[108:111]
	v_mfma_f32_16x16x32_bf16 v[108:111], v[204:207], v[162:165], v[108:111]
	s_barrier
	s_setprio 0
	s_mov_b32 m0, s26
	v_lshl_add_u64 v[216:217], s[18:19], 0, v[136:137]
	ds_read_b128 v[162:165], v144 offset:16384
	ds_read_b128 v[166:169], v144 offset:17408
	ds_read_b128 v[170:173], v144 offset:18432
	ds_read_b128 v[174:177], v144 offset:19456
	ds_read_b128 v[178:181], v144 offset:20480
	ds_read_b128 v[182:185], v144 offset:21504
	ds_read_b128 v[186:189], v144 offset:22528
	ds_read_b128 v[190:193], v144 offset:23552
	global_load_lds_dwordx4 v[216:217], off
	v_lshl_add_u64 v[218:219], s[18:19], 0, v[134:135]
	s_mov_b32 m0, s27
	s_nop 0
	global_load_lds_dwordx4 v[218:219], off
	s_waitcnt vmcnt(10)
	s_setprio 1
	s_barrier
	s_waitcnt lgkmcnt(0)
	v_mfma_f32_16x16x32_bf16 v[64:67], v[146:149], v[162:165], v[64:67]
	v_mfma_f32_16x16x32_bf16 v[64:67], v[150:153], v[166:169], v[64:67]
	v_mfma_f32_16x16x32_bf16 v[56:59], v[150:153], v[174:177], v[56:59]
	v_mfma_f32_16x16x32_bf16 v[56:59], v[146:149], v[170:173], v[56:59]
	v_mfma_f32_16x16x32_bf16 v[40:43], v[146:149], v[178:181], v[40:43]
	v_mfma_f32_16x16x32_bf16 v[40:43], v[150:153], v[182:185], v[40:43]
	v_mfma_f32_16x16x32_bf16 v[24:27], v[150:153], v[190:193], v[24:27]
	v_mfma_f32_16x16x32_bf16 v[24:27], v[146:149], v[186:189], v[24:27]
	v_mfma_f32_16x16x32_bf16 v[20:23], v[154:157], v[186:189], v[20:23]
	v_mfma_f32_16x16x32_bf16 v[20:23], v[158:161], v[190:193], v[20:23]
	v_mfma_f32_16x16x32_bf16 v[36:39], v[158:161], v[182:185], v[36:39]
	v_mfma_f32_16x16x32_bf16 v[36:39], v[154:157], v[178:181], v[36:39]
	v_mfma_f32_16x16x32_bf16 v[52:55], v[154:157], v[170:173], v[52:55]
	v_mfma_f32_16x16x32_bf16 v[52:55], v[158:161], v[174:177], v[52:55]
	v_mfma_f32_16x16x32_bf16 v[60:63], v[158:161], v[166:169], v[60:63]
	v_mfma_f32_16x16x32_bf16 v[60:63], v[154:157], v[162:165], v[60:63]
	s_barrier
	s_setprio 0
	s_add_u32 s42, s16, 0x8000
	s_addc_u32 s43, s17, 0
	s_add_i32 s41, s44, s25
	s_mov_b32 m0, s41
	s_nop 0
	global_load_lds_dwordx4 v2, s[42:43]
	s_add_i32 m0, s41, 0x2000
	s_nop 0
	global_load_lds_dwordx4 v132, s[42:43]
	s_add_i32 s41, 0, 0x18000
	v_add_u32_e32 v145, s41, v142
	ds_read_b128 v[146:149], v145
	ds_read_b128 v[150:153], v145 offset:1024
	ds_read_b128 v[154:157], v145 offset:2048
	ds_read_b128 v[158:161], v145 offset:3072
	s_waitcnt vmcnt(6)
	s_setprio 1
	s_barrier
	v_mfma_f32_16x16x32_bf16 v[48:51], v[194:197], v[162:165], v[48:51]
	v_mfma_f32_16x16x32_bf16 v[48:51], v[200:203], v[166:169], v[48:51]
	v_mfma_f32_16x16x32_bf16 v[32:35], v[200:203], v[174:177], v[32:35]
	v_mfma_f32_16x16x32_bf16 v[32:35], v[194:197], v[170:173], v[32:35]
	v_mfma_f32_16x16x32_bf16 v[16:19], v[194:197], v[178:181], v[16:19]
	v_mfma_f32_16x16x32_bf16 v[16:19], v[200:203], v[182:185], v[16:19]
	v_mfma_f32_16x16x32_bf16 v[8:11], v[200:203], v[190:193], v[8:11]
	v_mfma_f32_16x16x32_bf16 v[8:11], v[194:197], v[186:189], v[8:11]
	v_mfma_f32_16x16x32_bf16 v[4:7], v[204:207], v[186:189], v[4:7]
	v_mfma_f32_16x16x32_bf16 v[4:7], v[208:211], v[190:193], v[4:7]
	v_mfma_f32_16x16x32_bf16 v[12:15], v[208:211], v[182:185], v[12:15]
	v_mfma_f32_16x16x32_bf16 v[12:15], v[204:207], v[178:181], v[12:15]
	v_mfma_f32_16x16x32_bf16 v[28:31], v[204:207], v[170:173], v[28:31]
	v_mfma_f32_16x16x32_bf16 v[28:31], v[208:211], v[174:177], v[28:31]
	v_mfma_f32_16x16x32_bf16 v[44:47], v[208:211], v[166:169], v[44:47]
	v_mfma_f32_16x16x32_bf16 v[44:47], v[204:207], v[162:165], v[44:47]
	s_barrier
	s_setprio 0
	s_add_u32 s18, s18, 0x20000
	s_addc_u32 s19, s19, 0
	s_mov_b32 m0, s28
	ds_read_b128 v[162:165], v144 offset:32768
	ds_read_b128 v[166:169], v144 offset:33792
	ds_read_b128 v[170:173], v144 offset:34816
	ds_read_b128 v[174:177], v144 offset:35840
	ds_read_b128 v[178:181], v144 offset:36864
	ds_read_b128 v[182:185], v144 offset:37888
	ds_read_b128 v[186:189], v144 offset:38912
	ds_read_b128 v[190:193], v144 offset:39936
	global_load_lds_dwordx4 v136, s[18:19]
	s_mov_b32 m0, s29
	s_nop 0
	global_load_lds_dwordx4 v134, s[18:19]
	s_waitcnt lgkmcnt(8)
	s_setprio 1
	s_barrier
	s_waitcnt lgkmcnt(0)
	v_mfma_f32_16x16x32_bf16 v[128:131], v[146:149], v[162:165], v[128:131]
	v_mfma_f32_16x16x32_bf16 v[128:131], v[150:153], v[166:169], v[128:131]
	v_mfma_f32_16x16x32_bf16 v[120:123], v[150:153], v[174:177], v[120:123]
	v_mfma_f32_16x16x32_bf16 v[120:123], v[146:149], v[170:173], v[120:123]
	v_mfma_f32_16x16x32_bf16 v[104:107], v[146:149], v[178:181], v[104:107]
	v_mfma_f32_16x16x32_bf16 v[104:107], v[150:153], v[182:185], v[104:107]
	v_mfma_f32_16x16x32_bf16 v[88:91], v[150:153], v[190:193], v[88:91]
	v_mfma_f32_16x16x32_bf16 v[88:91], v[146:149], v[186:189], v[88:91]
	v_mfma_f32_16x16x32_bf16 v[84:87], v[154:157], v[186:189], v[84:87]
	v_mfma_f32_16x16x32_bf16 v[84:87], v[158:161], v[190:193], v[84:87]
	v_mfma_f32_16x16x32_bf16 v[100:103], v[158:161], v[182:185], v[100:103]
	v_mfma_f32_16x16x32_bf16 v[100:103], v[154:157], v[178:181], v[100:103]
	v_mfma_f32_16x16x32_bf16 v[116:119], v[154:157], v[170:173], v[116:119]
	v_mfma_f32_16x16x32_bf16 v[116:119], v[158:161], v[174:177], v[116:119]
	v_mfma_f32_16x16x32_bf16 v[124:127], v[158:161], v[166:169], v[124:127]
	v_mfma_f32_16x16x32_bf16 v[124:127], v[154:157], v[162:165], v[124:127]
	s_barrier
	s_setprio 0
	s_add_i32 s18, 0, 0x1c000
	s_add_i32 s19, s41, s25
	v_add_u32_e32 v145, s18, v142
	v_lshl_add_u64 v[212:213], v[212:213], 0, s[2:3]
	s_mov_b32 m0, s19
	ds_read_b128 v[194:197], v145
	ds_read_b128 v[200:203], v145 offset:1024
	ds_read_b128 v[204:207], v145 offset:2048
	ds_read_b128 v[208:211], v145 offset:3072
	global_load_lds_dwordx4 v[212:213], off
	v_lshl_add_u64 v[212:213], v[214:215], 0, s[2:3]
	s_add_i32 m0, s19, 0x2000
	s_nop 0
	global_load_lds_dwordx4 v[212:213], off
	s_setprio 1
	s_barrier
	s_waitcnt lgkmcnt(0)
	v_mfma_f32_16x16x32_bf16 v[112:115], v[194:197], v[162:165], v[112:115]
	v_mfma_f32_16x16x32_bf16 v[112:115], v[200:203], v[166:169], v[112:115]
	v_mfma_f32_16x16x32_bf16 v[96:99], v[200:203], v[174:177], v[96:99]
	v_mfma_f32_16x16x32_bf16 v[96:99], v[194:197], v[170:173], v[96:99]
	v_mfma_f32_16x16x32_bf16 v[80:83], v[194:197], v[178:181], v[80:83]
	v_mfma_f32_16x16x32_bf16 v[80:83], v[200:203], v[182:185], v[80:83]
	v_mfma_f32_16x16x32_bf16 v[72:75], v[200:203], v[190:193], v[72:75]
	v_mfma_f32_16x16x32_bf16 v[72:75], v[194:197], v[186:189], v[72:75]
	v_mfma_f32_16x16x32_bf16 v[68:71], v[204:207], v[186:189], v[68:71]
	v_mfma_f32_16x16x32_bf16 v[68:71], v[208:211], v[190:193], v[68:71]
	v_mfma_f32_16x16x32_bf16 v[76:79], v[208:211], v[182:185], v[76:79]
	v_mfma_f32_16x16x32_bf16 v[76:79], v[204:207], v[178:181], v[76:79]
	v_mfma_f32_16x16x32_bf16 v[92:95], v[204:207], v[170:173], v[92:95]
	v_mfma_f32_16x16x32_bf16 v[92:95], v[208:211], v[174:177], v[92:95]
	v_mfma_f32_16x16x32_bf16 v[108:111], v[208:211], v[166:169], v[108:111]
	v_mfma_f32_16x16x32_bf16 v[108:111], v[204:207], v[162:165], v[108:111]
	s_barrier
	s_setprio 0
	s_mov_b32 m0, s30
	v_lshl_add_u64 v[212:213], v[216:217], 0, s[2:3]
	ds_read_b128 v[162:165], v144 offset:49152
	ds_read_b128 v[166:169], v144 offset:50176
	ds_read_b128 v[170:173], v144 offset:51200
	ds_read_b128 v[174:177], v144 offset:52224
	ds_read_b128 v[178:181], v144 offset:53248
	ds_read_b128 v[182:185], v144 offset:54272
	ds_read_b128 v[186:189], v144 offset:55296
	ds_read_b128 v[190:193], v144 offset:56320
	global_load_lds_dwordx4 v[212:213], off
	v_lshl_add_u64 v[212:213], v[218:219], 0, s[2:3]
	s_mov_b32 m0, s31
	s_nop 0
	global_load_lds_dwordx4 v[212:213], off
	s_setprio 1
	s_barrier
	s_waitcnt lgkmcnt(0)
	v_mfma_f32_16x16x32_bf16 v[64:67], v[146:149], v[162:165], v[64:67]
	v_mfma_f32_16x16x32_bf16 v[64:67], v[150:153], v[166:169], v[64:67]
	v_mfma_f32_16x16x32_bf16 v[56:59], v[150:153], v[174:177], v[56:59]
	v_mfma_f32_16x16x32_bf16 v[56:59], v[146:149], v[170:173], v[56:59]
	v_mfma_f32_16x16x32_bf16 v[40:43], v[146:149], v[178:181], v[40:43]
	v_mfma_f32_16x16x32_bf16 v[40:43], v[150:153], v[182:185], v[40:43]
	v_mfma_f32_16x16x32_bf16 v[24:27], v[150:153], v[190:193], v[24:27]
	v_mfma_f32_16x16x32_bf16 v[24:27], v[146:149], v[186:189], v[24:27]
	v_mfma_f32_16x16x32_bf16 v[20:23], v[154:157], v[186:189], v[20:23]
	v_mfma_f32_16x16x32_bf16 v[20:23], v[158:161], v[190:193], v[20:23]
	v_mfma_f32_16x16x32_bf16 v[36:39], v[158:161], v[182:185], v[36:39]
	v_mfma_f32_16x16x32_bf16 v[36:39], v[154:157], v[178:181], v[36:39]
	v_mfma_f32_16x16x32_bf16 v[52:55], v[154:157], v[170:173], v[52:55]
	v_mfma_f32_16x16x32_bf16 v[52:55], v[158:161], v[174:177], v[52:55]
	v_mfma_f32_16x16x32_bf16 v[60:63], v[158:161], v[166:169], v[60:63]
	v_mfma_f32_16x16x32_bf16 v[60:63], v[154:157], v[162:165], v[60:63]
	s_barrier
	s_setprio 0
	s_add_u32 s16, s16, 0x8080
	s_addc_u32 s17, s17, 0
	s_add_i32 s18, s18, s25
	s_mov_b32 m0, s18
	s_nop 0
	global_load_lds_dwordx4 v2, s[16:17]
	s_add_i32 m0, s18, 0x2000
	s_nop 0
	global_load_lds_dwordx4 v132, s[16:17]
	s_waitcnt vmcnt(6)
	s_setprio 1
	s_barrier
	v_mfma_f32_16x16x32_bf16 v[48:51], v[194:197], v[162:165], v[48:51]
	v_mfma_f32_16x16x32_bf16 v[48:51], v[200:203], v[166:169], v[48:51]
	v_mfma_f32_16x16x32_bf16 v[32:35], v[200:203], v[174:177], v[32:35]
	v_mfma_f32_16x16x32_bf16 v[32:35], v[194:197], v[170:173], v[32:35]
	v_mfma_f32_16x16x32_bf16 v[16:19], v[194:197], v[178:181], v[16:19]
	v_mfma_f32_16x16x32_bf16 v[16:19], v[200:203], v[182:185], v[16:19]
	v_mfma_f32_16x16x32_bf16 v[8:11], v[200:203], v[190:193], v[8:11]
	v_mfma_f32_16x16x32_bf16 v[8:11], v[194:197], v[186:189], v[8:11]
	v_mfma_f32_16x16x32_bf16 v[4:7], v[204:207], v[186:189], v[4:7]
	v_mfma_f32_16x16x32_bf16 v[4:7], v[208:211], v[190:193], v[4:7]
	v_mfma_f32_16x16x32_bf16 v[12:15], v[208:211], v[182:185], v[12:15]
	v_mfma_f32_16x16x32_bf16 v[12:15], v[204:207], v[178:181], v[12:15]
	v_mfma_f32_16x16x32_bf16 v[28:31], v[204:207], v[170:173], v[28:31]
	v_mfma_f32_16x16x32_bf16 v[28:31], v[208:211], v[174:177], v[28:31]
	v_mfma_f32_16x16x32_bf16 v[44:47], v[208:211], v[166:169], v[44:47]
	v_mfma_f32_16x16x32_bf16 v[44:47], v[204:207], v[162:165], v[44:47]
	s_barrier
	s_setprio 0
	s_add_i32 s40, s40, 2
	s_add_u32 s14, s14, 0x100
	s_addc_u32 s15, s15, 0
	s_add_u32 s38, s38, 0x100
	s_addc_u32 s39, s39, 0
	s_cmp_gt_u32 s40, 5
	s_cbranch_scc0 .LBB0_236
	v_lshl_add_u32 v146, s35, 8, v1
	v_lshl_or_b32 v148, s34, 8, v143
	v_ashrrev_i32_e32 v147, 31, v146
	v_ashrrev_i32_e32 v149, 31, v148
	v_lshlrev_b64 v[150:151], 12, v[146:147]
	v_lshl_add_u64 v[150:151], s[4:5], 0, v[150:151]
	v_lshlrev_b64 v[148:149], 1, v[148:149]
	v_lshl_add_u64 v[150:151], v[150:151], 0, v[148:149]
	s_mov_b32 s7, 0x80000
	s_mov_b64 s[14:15], 0x80000
	v_cvt_pk_bf16_f32 v64, v64, v65
	v_cvt_pk_bf16_f32 v65, v66, v67
	v_cvt_pk_bf16_f32 v66, v60, v61
	v_add_co_u32_e32 v60, vcc, s7, v150
	v_cvt_pk_bf16_f32 v72, v72, v73
	v_cvt_pk_bf16_f32 v73, v74, v75
	v_cvt_pk_bf16_f32 v74, v68, v69
	v_lshl_add_u64 v[68:69], v[150:151], 0, s[14:15]
	v_addc_co_u32_e32 v61, vcc, 0, v151, vcc
	v_cvt_pk_bf16_f32 v48, v48, v49
	v_cvt_pk_bf16_f32 v49, v50, v51
	v_cvt_pk_bf16_f32 v50, v44, v45
	v_cvt_pk_bf16_f32 v51, v46, v47
	s_mov_b32 s7, 0x90000
	v_cvt_pk_bf16_f32 v112, v112, v113
	v_cvt_pk_bf16_f32 v113, v114, v115
	v_cvt_pk_bf16_f32 v114, v108, v109
	v_or_b32_e32 v108, 16, v146
	global_store_dwordx4 v[68:69], v[48:51], off offset:64
	s_mov_b64 s[14:15], 0x90000
	v_ashrrev_i32_e32 v109, 31, v108
	v_add_co_u32_e32 v50, vcc, s7, v150
	v_cvt_pk_bf16_f32 v96, v96, v97
	v_cvt_pk_bf16_f32 v97, v98, v99
	v_cvt_pk_bf16_f32 v98, v92, v93
	v_or_b32_e32 v92, 32, v146
	v_lshl_add_u64 v[48:49], v[150:151], 0, s[14:15]
	v_addc_co_u32_e32 v51, vcc, 0, v151, vcc
	v_cvt_pk_bf16_f32 v32, v32, v33
	v_cvt_pk_bf16_f32 v33, v34, v35
	v_cvt_pk_bf16_f32 v34, v28, v29
	v_cvt_pk_bf16_f32 v35, v30, v31
	s_mov_b32 s7, 0xa0000
	v_lshlrev_b64 v[108:109], 12, v[108:109]
	v_ashrrev_i32_e32 v93, 31, v92
	v_cvt_pk_bf16_f32 v80, v80, v81
	v_cvt_pk_bf16_f32 v81, v82, v83
	v_cvt_pk_bf16_f32 v82, v76, v77
	v_or_b32_e32 v76, 48, v146
	global_store_dwordx4 v[48:49], v[32:35], off offset:64
	s_mov_b64 s[14:15], 0xa0000
	v_cvt_pk_bf16_f32 v115, v110, v111
	v_add_co_u32_e32 v34, vcc, s7, v150
	v_lshl_add_u64 v[108:109], s[4:5], 0, v[108:109]
	v_lshlrev_b64 v[92:93], 12, v[92:93]
	v_ashrrev_i32_e32 v77, 31, v76
	v_lshl_add_u64 v[32:33], v[150:151], 0, s[14:15]
	v_addc_co_u32_e32 v35, vcc, 0, v151, vcc
	v_cvt_pk_bf16_f32 v16, v16, v17
	v_cvt_pk_bf16_f32 v17, v18, v19
	v_cvt_pk_bf16_f32 v18, v12, v13
	v_cvt_pk_bf16_f32 v19, v14, v15
	s_mov_b32 s7, 0xb0000
	global_store_dwordx4 v[150:151], v[112:115], off offset:64
	v_cvt_pk_bf16_f32 v99, v94, v95
	v_lshl_add_u64 v[92:93], s[4:5], 0, v[92:93]
	v_lshl_add_u64 v[112:113], v[108:109], 0, v[148:149]
	v_lshlrev_b64 v[76:77], 12, v[76:77]
	global_store_dwordx4 v[32:33], v[16:19], off offset:64
	global_store_dwordx4 v[112:113], v[96:99], off offset:64
	v_cvt_pk_bf16_f32 v83, v78, v79
	v_add_co_u32_e32 v18, vcc, s7, v150
	v_lshl_add_u64 v[96:97], v[92:93], 0, v[148:149]
	v_lshl_add_u64 v[76:77], s[4:5], 0, v[76:77]
	s_mov_b64 s[14:15], 0xb0000
	v_addc_co_u32_e32 v19, vcc, 0, v151, vcc
	v_cvt_pk_bf16_f32 v128, v128, v129
	v_cvt_pk_bf16_f32 v129, v130, v131
	v_cvt_pk_bf16_f32 v130, v124, v125
	v_cvt_pk_bf16_f32 v131, v126, v127
	v_cvt_pk_bf16_f32 v108, v120, v121
	v_cvt_pk_bf16_f32 v109, v122, v123
	v_cvt_pk_bf16_f32 v110, v116, v117
	v_cvt_pk_bf16_f32 v111, v118, v119
	v_cvt_pk_bf16_f32 v92, v104, v105
	v_cvt_pk_bf16_f32 v93, v106, v107
	v_cvt_pk_bf16_f32 v94, v100, v101
	v_cvt_pk_bf16_f32 v95, v102, v103
	global_store_dwordx4 v[96:97], v[80:83], off offset:64
	v_cvt_pk_bf16_f32 v78, v84, v85
	v_cvt_pk_bf16_f32 v79, v86, v87
	v_lshl_add_u64 v[80:81], v[76:77], 0, v[148:149]
	v_cvt_pk_bf16_f32 v76, v88, v89
	v_cvt_pk_bf16_f32 v77, v90, v91
	v_cvt_pk_bf16_f32 v75, v70, v71
	v_cvt_pk_bf16_f32 v67, v62, v63
	v_cvt_pk_bf16_f32 v44, v56, v57
	v_cvt_pk_bf16_f32 v45, v58, v59
	v_cvt_pk_bf16_f32 v46, v52, v53
	v_cvt_pk_bf16_f32 v47, v54, v55
	v_cvt_pk_bf16_f32 v28, v40, v41
	v_cvt_pk_bf16_f32 v29, v42, v43
	v_cvt_pk_bf16_f32 v30, v36, v37
	v_cvt_pk_bf16_f32 v31, v38, v39
	v_lshl_add_u64 v[16:17], v[150:151], 0, s[14:15]
	v_cvt_pk_bf16_f32 v12, v24, v25
	v_cvt_pk_bf16_f32 v13, v26, v27
	v_cvt_pk_bf16_f32 v14, v20, v21
	v_cvt_pk_bf16_f32 v15, v22, v23
	v_cvt_pk_bf16_f32 v8, v8, v9
	v_cvt_pk_bf16_f32 v9, v10, v11
	v_cvt_pk_bf16_f32 v10, v4, v5
	v_cvt_pk_bf16_f32 v11, v6, v7
	s_and_b64 vcc, exec, s[0:1]
	s_mov_b32 s34, s6
	s_mov_b32 s35, s8
	s_mov_b64 s[16:17], s[12:13]
	s_mov_b64 s[14:15], s[10:11]
	global_store_dwordx4 v[150:151], v[128:131], off
	global_store_dwordx4 v[112:113], v[108:111], off
	global_store_dwordx4 v[96:97], v[92:95], off
	global_store_dwordx4 v[80:81], v[76:79], off
	global_store_dwordx4 v[80:81], v[72:75], off offset:64
	global_store_dwordx4 v[60:61], v[64:67], off
	global_store_dwordx4 v[50:51], v[44:47], off
	global_store_dwordx4 v[34:35], v[28:31], off
	global_store_dwordx4 v[18:19], v[12:15], off
	global_store_dwordx4 v[16:17], v[8:11], off offset:64
	s_cbranch_vccz .LBB0_233
	s_waitcnt vmcnt(0)
	s_cmpk_gt_u32 s20, 0xff
	s_cbranch_scc1 .LBB0_240
	s_barrier

.LBB0_816:
	s_add_u32 s18, s16, 0x100
	s_addc_u32 s19, s17, 0
	s_cmpk_eq_i32 s14, 0x2e00
	s_cselect_b32 s23, s1, s19
	s_cselect_b32 s22, s0, s18
	s_cselect_b32 s21, s7, s42
	s_cselect_b32 s20, s6, s41
	s_add_i32 s33, 0, 0x10000
	v_add_u32_e32 v2, s33, v200
	ds_read_b128 v[62:65], v2
	ds_read_b128 v[74:77], v2 offset:1024
	ds_read_b128 v[82:85], v2 offset:2048
	ds_read_b128 v[94:97], v2 offset:3072
	s_add_i32 m0, s30, 0xc000
	ds_read_b128 v[106:109], v202
	ds_read_b128 v[118:121], v202 offset:1024
	ds_read_b128 v[130:133], v202 offset:2048
	ds_read_b128 v[142:145], v202 offset:3072
	ds_read_b128 v[150:153], v202 offset:4096
	ds_read_b128 v[162:165], v202 offset:5120
	ds_read_b128 v[174:177], v202 offset:6144
	ds_read_b128 v[178:181], v202 offset:7168
	global_load_lds_dwordx4 v212, s[16:17]
	s_add_i32 m0, s30, 0xe000
	s_nop 0
	global_load_lds_dwordx4 v214, s[16:17]
	s_waitcnt lgkmcnt(8)
	s_setprio 1
	s_barrier
	s_waitcnt lgkmcnt(0)
	v_mfma_f32_16x16x32_bf16 v[170:173], v[62:65], v[106:109], v[170:173]
	v_mfma_f32_16x16x32_bf16 v[170:173], v[74:77], v[118:121], v[170:173]
	v_mfma_f32_16x16x32_bf16 v[146:149], v[74:77], v[142:145], v[146:149]
	v_mfma_f32_16x16x32_bf16 v[146:149], v[62:65], v[130:133], v[146:149]
	v_mfma_f32_16x16x32_bf16 v[122:125], v[62:65], v[150:153], v[122:125]
	v_mfma_f32_16x16x32_bf16 v[122:125], v[74:77], v[162:165], v[122:125]
	v_mfma_f32_16x16x32_bf16 v[98:101], v[74:77], v[178:181], v[98:101]
	v_mfma_f32_16x16x32_bf16 v[98:101], v[62:65], v[174:177], v[98:101]
	v_mfma_f32_16x16x32_bf16 v[90:93], v[82:85], v[174:177], v[90:93]
	v_mfma_f32_16x16x32_bf16 v[90:93], v[94:97], v[178:181], v[90:93]
	v_mfma_f32_16x16x32_bf16 v[114:117], v[94:97], v[162:165], v[114:117]
	v_mfma_f32_16x16x32_bf16 v[114:117], v[82:85], v[150:153], v[114:117]
	v_mfma_f32_16x16x32_bf16 v[138:141], v[82:85], v[130:133], v[138:141]
	v_mfma_f32_16x16x32_bf16 v[138:141], v[94:97], v[142:145], v[138:141]
	v_mfma_f32_16x16x32_bf16 v[166:169], v[94:97], v[118:121], v[166:169]
	v_mfma_f32_16x16x32_bf16 v[166:169], v[82:85], v[106:109], v[166:169]
	s_barrier
	s_setprio 0
	s_add_i32 s44, 0, 0x14000
	s_add_i32 s16, s33, s29
	v_add_u32_e32 v2, s44, v200
	v_lshl_add_u64 v[226:227], s[20:21], 0, v[208:209]
	s_mov_b32 m0, s16
	ds_read_b128 v[182:185], v2
	ds_read_b128 v[186:189], v2 offset:1024
	ds_read_b128 v[190:193], v2 offset:2048
	ds_read_b128 v[194:197], v2 offset:3072
	global_load_lds_dwordx4 v[226:227], off
	v_lshl_add_u64 v[228:229], s[20:21], 0, v[204:205]
	s_add_i32 m0, s16, 0x2000
	s_nop 0
	global_load_lds_dwordx4 v[228:229], off
	s_setprio 1
	s_barrier
	s_waitcnt lgkmcnt(0)
	v_mfma_f32_16x16x32_bf16 v[158:161], v[182:185], v[106:109], v[158:161]
	v_mfma_f32_16x16x32_bf16 v[158:161], v[186:189], v[118:121], v[158:161]
	v_mfma_f32_16x16x32_bf16 v[106:109], v[190:193], v[106:109], v[154:157]
	v_mfma_f32_16x16x32_bf16 v[106:109], v[194:197], v[118:121], v[106:109]
	v_mfma_f32_16x16x32_bf16 v[126:129], v[190:193], v[130:133], v[126:129]
	v_mfma_f32_16x16x32_bf16 v[126:129], v[194:197], v[142:145], v[126:129]
	v_mfma_f32_16x16x32_bf16 v[110:113], v[182:185], v[150:153], v[110:113]
	v_mfma_f32_16x16x32_bf16 v[110:113], v[186:189], v[162:165], v[110:113]
	v_mfma_f32_16x16x32_bf16 v[102:105], v[190:193], v[150:153], v[102:105]
	v_mfma_f32_16x16x32_bf16 v[102:105], v[194:197], v[162:165], v[102:105]
	v_mfma_f32_16x16x32_bf16 v[86:89], v[182:185], v[174:177], v[86:89]
	v_mfma_f32_16x16x32_bf16 v[86:89], v[186:189], v[178:181], v[86:89]
	v_mfma_f32_16x16x32_bf16 v[78:81], v[190:193], v[174:177], v[78:81]
	v_mfma_f32_16x16x32_bf16 v[78:81], v[194:197], v[178:181], v[78:81]
	v_mfma_f32_16x16x32_bf16 v[118:121], v[182:185], v[130:133], v[134:137]
	v_mfma_f32_16x16x32_bf16 v[118:121], v[186:189], v[142:145], v[118:121]
	s_barrier
	s_setprio 0
	s_mov_b32 m0, s30
	v_lshl_add_u64 v[230:231], s[22:23], 0, v[210:211]
	ds_read_b128 v[130:133], v202 offset:16384
	ds_read_b128 v[134:137], v202 offset:17408
	ds_read_b128 v[142:145], v202 offset:18432
	ds_read_b128 v[150:153], v202 offset:19456
	ds_read_b128 v[154:157], v202 offset:20480
	ds_read_b128 v[162:165], v202 offset:21504
	ds_read_b128 v[174:177], v202 offset:22528
	ds_read_b128 v[178:181], v202 offset:23552
	global_load_lds_dwordx4 v[230:231], off
	v_lshl_add_u64 v[232:233], s[22:23], 0, v[206:207]
	s_mov_b32 m0, s31
	s_nop 0
	global_load_lds_dwordx4 v[232:233], off
	s_waitcnt vmcnt(10)
	s_setprio 1
	s_barrier
	s_waitcnt lgkmcnt(0)
	v_mfma_f32_16x16x32_bf16 v[70:73], v[62:65], v[130:133], v[70:73]
	v_mfma_f32_16x16x32_bf16 v[70:73], v[74:77], v[134:137], v[70:73]
	v_mfma_f32_16x16x32_bf16 v[50:53], v[74:77], v[150:153], v[50:53]
	v_mfma_f32_16x16x32_bf16 v[50:53], v[62:65], v[142:145], v[50:53]
	v_mfma_f32_16x16x32_bf16 v[34:37], v[62:65], v[154:157], v[34:37]
	v_mfma_f32_16x16x32_bf16 v[34:37], v[74:77], v[162:165], v[34:37]
	v_mfma_f32_16x16x32_bf16 v[18:21], v[74:77], v[178:181], v[18:21]
	v_mfma_f32_16x16x32_bf16 v[18:21], v[62:65], v[174:177], v[18:21]
	v_mfma_f32_16x16x32_bf16 v[14:17], v[82:85], v[174:177], v[14:17]
	v_mfma_f32_16x16x32_bf16 v[14:17], v[94:97], v[178:181], v[14:17]
	v_mfma_f32_16x16x32_bf16 v[30:33], v[94:97], v[162:165], v[30:33]
	v_mfma_f32_16x16x32_bf16 v[30:33], v[82:85], v[154:157], v[30:33]
	v_mfma_f32_16x16x32_bf16 v[46:49], v[82:85], v[142:145], v[46:49]
	v_mfma_f32_16x16x32_bf16 v[46:49], v[94:97], v[150:153], v[46:49]
	v_mfma_f32_16x16x32_bf16 v[66:69], v[94:97], v[134:137], v[66:69]
	v_mfma_f32_16x16x32_bf16 v[66:69], v[82:85], v[130:133], v[66:69]
	s_barrier
	s_setprio 0
	s_add_u32 s16, s20, 0xc0000
	s_addc_u32 s17, s21, 0
	s_add_i32 s33, s44, s29
	s_mov_b32 m0, s33
	s_nop 0
	global_load_lds_dwordx4 v208, s[16:17]
	v_lshl_add_u64 v[4:5], s[16:17], 0, v[204:205]
	s_add_i32 m0, s33, 0x2000
	s_nop 0
	global_load_lds_dwordx4 v[4:5], off
	s_add_i32 s33, 0, 0x18000
	v_add_u32_e32 v2, s33, v200
	ds_read_b128 v[62:65], v2
	ds_read_b128 v[74:77], v2 offset:1024
	ds_read_b128 v[82:85], v2 offset:2048
	ds_read_b128 v[94:97], v2 offset:3072
	s_waitcnt vmcnt(6)
	s_setprio 1
	s_barrier
	v_mfma_f32_16x16x32_bf16 v[58:61], v[182:185], v[130:133], v[58:61]
	v_mfma_f32_16x16x32_bf16 v[58:61], v[186:189], v[134:137], v[58:61]
	v_mfma_f32_16x16x32_bf16 v[42:45], v[186:189], v[150:153], v[42:45]
	v_mfma_f32_16x16x32_bf16 v[42:45], v[182:185], v[142:145], v[42:45]
	v_mfma_f32_16x16x32_bf16 v[26:29], v[182:185], v[154:157], v[26:29]
	v_mfma_f32_16x16x32_bf16 v[26:29], v[186:189], v[162:165], v[26:29]
	v_mfma_f32_16x16x32_bf16 v[10:13], v[186:189], v[178:181], v[10:13]
	v_mfma_f32_16x16x32_bf16 v[10:13], v[182:185], v[174:177], v[10:13]
	v_mfma_f32_16x16x32_bf16 v[4:7], v[190:193], v[174:177], v[6:9]
	v_mfma_f32_16x16x32_bf16 v[4:7], v[194:197], v[178:181], v[4:7]
	v_mfma_f32_16x16x32_bf16 v[22:25], v[194:197], v[162:165], v[22:25]
	v_mfma_f32_16x16x32_bf16 v[22:25], v[190:193], v[154:157], v[22:25]
	v_mfma_f32_16x16x32_bf16 v[38:41], v[190:193], v[142:145], v[38:41]
	v_mfma_f32_16x16x32_bf16 v[38:41], v[194:197], v[150:153], v[38:41]
	v_mfma_f32_16x16x32_bf16 v[54:57], v[194:197], v[134:137], v[54:57]
	v_mfma_f32_16x16x32_bf16 v[54:57], v[190:193], v[130:133], v[54:57]
	s_barrier
	s_setprio 0
	s_add_u32 s16, s22, 0xc0000
	s_addc_u32 s17, s23, 0
	s_mov_b32 m0, s34
	v_lshl_add_u64 v[8:9], s[16:17], 0, v[210:211]
	ds_read_b128 v[130:133], v202 offset:32768
	ds_read_b128 v[134:137], v202 offset:33792
	ds_read_b128 v[142:145], v202 offset:34816
	ds_read_b128 v[150:153], v202 offset:35840
	ds_read_b128 v[162:165], v202 offset:36864
	ds_read_b128 v[174:177], v202 offset:37888
	ds_read_b128 v[178:181], v202 offset:38912
	ds_read_b128 v[182:185], v202 offset:39936
	global_load_lds_dwordx4 v[8:9], off
	v_lshl_add_u64 v[8:9], s[16:17], 0, v[206:207]
	s_mov_b32 m0, s35
	s_nop 0
	global_load_lds_dwordx4 v[8:9], off
	s_waitcnt lgkmcnt(8)
	s_setprio 1
	s_barrier
	s_waitcnt lgkmcnt(0)
	v_mfma_f32_16x16x32_bf16 v[154:157], v[62:65], v[130:133], v[170:173]
	v_mfma_f32_16x16x32_bf16 v[170:173], v[74:77], v[134:137], v[154:157]
	v_mfma_f32_16x16x32_bf16 v[154:157], v[82:85], v[130:133], v[166:169]
	v_mfma_f32_16x16x32_bf16 v[166:169], v[94:97], v[134:137], v[154:157]
	v_mfma_f32_16x16x32_bf16 v[146:149], v[62:65], v[142:145], v[146:149]
	v_mfma_f32_16x16x32_bf16 v[146:149], v[74:77], v[150:153], v[146:149]
	v_mfma_f32_16x16x32_bf16 v[138:141], v[82:85], v[142:145], v[138:141]
	v_mfma_f32_16x16x32_bf16 v[138:141], v[94:97], v[150:153], v[138:141]
	v_mfma_f32_16x16x32_bf16 v[122:125], v[62:65], v[162:165], v[122:125]
	v_mfma_f32_16x16x32_bf16 v[122:125], v[74:77], v[174:177], v[122:125]
	v_mfma_f32_16x16x32_bf16 v[114:117], v[82:85], v[162:165], v[114:117]
	v_mfma_f32_16x16x32_bf16 v[114:117], v[94:97], v[174:177], v[114:117]
	v_mfma_f32_16x16x32_bf16 v[98:101], v[62:65], v[178:181], v[98:101]
	v_mfma_f32_16x16x32_bf16 v[98:101], v[74:77], v[182:185], v[98:101]
	v_mfma_f32_16x16x32_bf16 v[90:93], v[82:85], v[178:181], v[90:93]
	v_mfma_f32_16x16x32_bf16 v[90:93], v[94:97], v[182:185], v[90:93]
	s_barrier
	s_setprio 0
	s_add_i32 s22, 0, 0x1c000
	s_add_i32 s16, s33, s29
	v_add_u32_e32 v2, s22, v200
	v_lshl_add_u64 v[8:9], v[226:227], 0, s[2:3]
	s_mov_b32 m0, s16
	ds_read_b128 v[186:189], v2
	ds_read_b128 v[190:193], v2 offset:1024
	ds_read_b128 v[194:197], v2 offset:2048
	ds_read_b128 v[220:223], v2 offset:3072
	global_load_lds_dwordx4 v[8:9], off
	v_lshl_add_u64 v[8:9], v[228:229], 0, s[2:3]
	s_add_i32 m0, s16, 0x2000
	s_nop 0
	global_load_lds_dwordx4 v[8:9], off
	s_setprio 1
	s_barrier
	s_waitcnt lgkmcnt(0)
	v_mfma_f32_16x16x32_bf16 v[154:157], v[186:189], v[130:133], v[158:161]
	v_mfma_f32_16x16x32_bf16 v[158:161], v[190:193], v[134:137], v[154:157]
	v_mfma_f32_16x16x32_bf16 v[106:109], v[194:197], v[130:133], v[106:109]
	v_mfma_f32_16x16x32_bf16 v[154:157], v[220:223], v[134:137], v[106:109]
	v_mfma_f32_16x16x32_bf16 v[106:109], v[186:189], v[142:145], v[118:121]
	v_mfma_f32_16x16x32_bf16 v[134:137], v[190:193], v[150:153], v[106:109]
	v_mfma_f32_16x16x32_bf16 v[106:109], v[194:197], v[142:145], v[126:129]
	v_mfma_f32_16x16x32_bf16 v[126:129], v[220:223], v[150:153], v[106:109]
	v_mfma_f32_16x16x32_bf16 v[106:109], v[186:189], v[162:165], v[110:113]
	v_mfma_f32_16x16x32_bf16 v[110:113], v[190:193], v[174:177], v[106:109]
	v_mfma_f32_16x16x32_bf16 v[102:105], v[194:197], v[162:165], v[102:105]
	v_mfma_f32_16x16x32_bf16 v[102:105], v[220:223], v[174:177], v[102:105]
	v_mfma_f32_16x16x32_bf16 v[86:89], v[186:189], v[178:181], v[86:89]
	v_mfma_f32_16x16x32_bf16 v[86:89], v[190:193], v[182:185], v[86:89]
	v_mfma_f32_16x16x32_bf16 v[78:81], v[194:197], v[178:181], v[78:81]
	v_mfma_f32_16x16x32_bf16 v[78:81], v[220:223], v[182:185], v[78:81]
	s_barrier
	s_setprio 0
	s_mov_b32 m0, s36
	v_lshl_add_u64 v[8:9], v[230:231], 0, s[2:3]
	ds_read_b128 v[106:109], v202 offset:49152
	ds_read_b128 v[118:121], v202 offset:50176
	ds_read_b128 v[130:133], v202 offset:51200
	ds_read_b128 v[142:145], v202 offset:52224
	ds_read_b128 v[150:153], v202 offset:53248
	ds_read_b128 v[162:165], v202 offset:54272
	ds_read_b128 v[174:177], v202 offset:55296
	ds_read_b128 v[178:181], v202 offset:56320
	global_load_lds_dwordx4 v[8:9], off
	v_lshl_add_u64 v[8:9], v[232:233], 0, s[2:3]
	s_mov_b32 m0, s37
	s_nop 0
	global_load_lds_dwordx4 v[8:9], off
	s_setprio 1
	s_barrier
	s_waitcnt lgkmcnt(0)
	v_mfma_f32_16x16x32_bf16 v[70:73], v[62:65], v[106:109], v[70:73]
	v_mfma_f32_16x16x32_bf16 v[70:73], v[74:77], v[118:121], v[70:73]
	v_mfma_f32_16x16x32_bf16 v[50:53], v[74:77], v[142:145], v[50:53]
	v_mfma_f32_16x16x32_bf16 v[50:53], v[62:65], v[130:133], v[50:53]
	v_mfma_f32_16x16x32_bf16 v[34:37], v[62:65], v[150:153], v[34:37]
	v_mfma_f32_16x16x32_bf16 v[34:37], v[74:77], v[162:165], v[34:37]
	v_mfma_f32_16x16x32_bf16 v[18:21], v[74:77], v[178:181], v[18:21]
	v_mfma_f32_16x16x32_bf16 v[18:21], v[62:65], v[174:177], v[18:21]
	v_mfma_f32_16x16x32_bf16 v[14:17], v[82:85], v[174:177], v[14:17]
	v_mfma_f32_16x16x32_bf16 v[14:17], v[94:97], v[178:181], v[14:17]
	v_mfma_f32_16x16x32_bf16 v[30:33], v[94:97], v[162:165], v[30:33]
	v_mfma_f32_16x16x32_bf16 v[30:33], v[82:85], v[150:153], v[30:33]
	v_mfma_f32_16x16x32_bf16 v[46:49], v[82:85], v[130:133], v[46:49]
	v_mfma_f32_16x16x32_bf16 v[46:49], v[94:97], v[142:145], v[46:49]
	v_mfma_f32_16x16x32_bf16 v[66:69], v[94:97], v[118:121], v[66:69]
	v_mfma_f32_16x16x32_bf16 v[66:69], v[82:85], v[106:109], v[66:69]
	s_barrier
	s_setprio 0
	s_add_u32 s16, s20, 0xc0080
	s_addc_u32 s17, s21, 0
	s_add_i32 s20, s22, s29
	v_lshl_add_u64 v[8:9], s[16:17], 0, v[208:209]
	s_mov_b32 m0, s20
	s_nop 0
	global_load_lds_dwordx4 v[8:9], off
	v_lshl_add_u64 v[8:9], s[16:17], 0, v[204:205]
	s_add_i32 m0, s20, 0x2000
	s_nop 0
	global_load_lds_dwordx4 v[8:9], off
	s_waitcnt vmcnt(6)
	s_setprio 1
	s_barrier
	v_mfma_f32_16x16x32_bf16 v[58:61], v[186:189], v[106:109], v[58:61]
	v_mfma_f32_16x16x32_bf16 v[58:61], v[190:193], v[118:121], v[58:61]
	v_mfma_f32_16x16x32_bf16 v[54:57], v[194:197], v[106:109], v[54:57]
	v_mfma_f32_16x16x32_bf16 v[54:57], v[220:223], v[118:121], v[54:57]
	v_mfma_f32_16x16x32_bf16 v[42:45], v[186:189], v[130:133], v[42:45]
	v_mfma_f32_16x16x32_bf16 v[42:45], v[190:193], v[142:145], v[42:45]
	v_mfma_f32_16x16x32_bf16 v[38:41], v[194:197], v[130:133], v[38:41]
	v_mfma_f32_16x16x32_bf16 v[38:41], v[220:223], v[142:145], v[38:41]
	v_mfma_f32_16x16x32_bf16 v[26:29], v[186:189], v[150:153], v[26:29]
	v_mfma_f32_16x16x32_bf16 v[26:29], v[190:193], v[162:165], v[26:29]
	v_mfma_f32_16x16x32_bf16 v[22:25], v[194:197], v[150:153], v[22:25]
	v_mfma_f32_16x16x32_bf16 v[22:25], v[220:223], v[162:165], v[22:25]
	v_mfma_f32_16x16x32_bf16 v[8:11], v[186:189], v[174:177], v[10:13]
	v_mfma_f32_16x16x32_bf16 v[10:13], v[190:193], v[178:181], v[8:11]
	v_mfma_f32_16x16x32_bf16 v[4:7], v[194:197], v[174:177], v[4:7]
	v_mfma_f32_16x16x32_bf16 v[6:9], v[220:223], v[178:181], v[4:7]
	s_barrier
	s_setprio 0
	s_add_u32 s14, s14, 0x200
	s_addc_u32 s15, s15, 0
	s_add_u32 s41, s41, 0x100
	s_addc_u32 s42, s42, 0
	s_cmp_gt_u32 s43, 45
	s_cbranch_scc1 .LBB0_806
	s_mov_b64 s[16:17], s[18:19]
	s_branch .LBB0_814

.LBB0_878:
	s_add_u32 s22, s20, 0xfff80080
	s_addc_u32 s23, s21, -1
	s_add_i32 s49, 0, 0x10000
	s_waitcnt vmcnt(0)
	v_add_u32_e32 v144, s49, v188
	ds_read_b128 v[132:135], v144
	ds_read_b128 v[136:139], v144 offset:1024
	ds_read_b128 v[140:143], v144 offset:2048
	ds_read_b128 v[144:147], v144 offset:3072
	s_cmp_eq_u32 s48, 28
	s_cselect_b32 s25, s15, s23
	s_cselect_b32 s24, s44, s22
	s_cselect_b32 s23, s13, s47
	s_cselect_b32 s22, s45, s46
	s_add_i32 m0, s34, 0xc000
	ds_read_b128 v[148:151], v190
	ds_read_b128 v[152:155], v190 offset:1024
	ds_read_b128 v[156:159], v190 offset:2048
	ds_read_b128 v[160:163], v190 offset:3072
	ds_read_b128 v[174:177], v190 offset:4096
	ds_read_b128 v[178:181], v190 offset:5120
	ds_read_b128 v[182:185], v190 offset:6144
	ds_read_b128 v[192:195], v190 offset:7168
	global_load_lds_dwordx4 v170, s[20:21]
	s_add_i32 m0, s34, 0xe000
	s_nop 0
	global_load_lds_dwordx4 v172, s[20:21]
	s_waitcnt lgkmcnt(8)
	s_setprio 1
	s_barrier
	s_waitcnt lgkmcnt(0)
	v_mfma_f32_16x16x32_bf16 v[128:131], v[132:135], v[148:151], v[128:131]
	v_mfma_f32_16x16x32_bf16 v[128:131], v[136:139], v[152:155], v[128:131]
	v_mfma_f32_16x16x32_bf16 v[120:123], v[136:139], v[160:163], v[120:123]
	v_mfma_f32_16x16x32_bf16 v[120:123], v[132:135], v[156:159], v[120:123]
	v_mfma_f32_16x16x32_bf16 v[96:99], v[132:135], v[174:177], v[96:99]
	v_mfma_f32_16x16x32_bf16 v[96:99], v[136:139], v[178:181], v[96:99]
	v_mfma_f32_16x16x32_bf16 v[88:91], v[136:139], v[192:195], v[88:91]
	v_mfma_f32_16x16x32_bf16 v[88:91], v[132:135], v[182:185], v[88:91]
	v_mfma_f32_16x16x32_bf16 v[84:87], v[140:143], v[182:185], v[84:87]
	v_mfma_f32_16x16x32_bf16 v[84:87], v[144:147], v[192:195], v[84:87]
	v_mfma_f32_16x16x32_bf16 v[92:95], v[144:147], v[178:181], v[92:95]
	v_mfma_f32_16x16x32_bf16 v[92:95], v[140:143], v[174:177], v[92:95]
	v_mfma_f32_16x16x32_bf16 v[116:119], v[140:143], v[156:159], v[116:119]
	v_mfma_f32_16x16x32_bf16 v[116:119], v[144:147], v[160:163], v[116:119]
	v_mfma_f32_16x16x32_bf16 v[124:127], v[144:147], v[152:155], v[124:127]
	v_mfma_f32_16x16x32_bf16 v[124:127], v[140:143], v[148:151], v[124:127]
	s_barrier
	s_setprio 0
	s_add_i32 s52, 0, 0x14000
	v_add_u32_e32 v186, s52, v188
	s_add_i32 s49, s49, s31
	ds_read_b128 v[200:203], v186
	ds_read_b128 v[204:207], v186 offset:1024
	ds_read_b128 v[208:211], v186 offset:2048
	ds_read_b128 v[212:215], v186 offset:3072
	v_lshl_add_u64 v[186:187], s[22:23], 0, v[2:3]
	s_mov_b32 m0, s49
	v_lshl_add_u64 v[196:197], s[22:23], 0, v[164:165]
	global_load_lds_dwordx4 v[186:187], off
	s_add_i32 m0, s49, 0x2000
	s_nop 0
	global_load_lds_dwordx4 v[196:197], off
	s_setprio 1
	s_barrier
	s_waitcnt lgkmcnt(0)
	v_mfma_f32_16x16x32_bf16 v[112:115], v[200:203], v[148:151], v[112:115]
	v_mfma_f32_16x16x32_bf16 v[112:115], v[204:207], v[152:155], v[112:115]
	v_mfma_f32_16x16x32_bf16 v[104:107], v[204:207], v[160:163], v[104:107]
	v_mfma_f32_16x16x32_bf16 v[104:107], v[200:203], v[156:159], v[104:107]
	v_mfma_f32_16x16x32_bf16 v[80:83], v[200:203], v[174:177], v[80:83]
	v_mfma_f32_16x16x32_bf16 v[80:83], v[204:207], v[178:181], v[80:83]
	v_mfma_f32_16x16x32_bf16 v[72:75], v[204:207], v[192:195], v[72:75]
	v_mfma_f32_16x16x32_bf16 v[72:75], v[200:203], v[182:185], v[72:75]
	v_mfma_f32_16x16x32_bf16 v[68:71], v[208:211], v[182:185], v[68:71]
	v_mfma_f32_16x16x32_bf16 v[68:71], v[212:215], v[192:195], v[68:71]
	v_mfma_f32_16x16x32_bf16 v[76:79], v[212:215], v[178:181], v[76:79]
	v_mfma_f32_16x16x32_bf16 v[76:79], v[208:211], v[174:177], v[76:79]
	v_mfma_f32_16x16x32_bf16 v[100:103], v[208:211], v[156:159], v[100:103]
	v_mfma_f32_16x16x32_bf16 v[100:103], v[212:215], v[160:163], v[100:103]
	v_mfma_f32_16x16x32_bf16 v[108:111], v[212:215], v[152:155], v[108:111]
	v_mfma_f32_16x16x32_bf16 v[108:111], v[208:211], v[148:151], v[108:111]
	s_barrier
	s_setprio 0
	s_mov_b32 m0, s34
	v_lshl_add_u64 v[216:217], s[24:25], 0, v[168:169]
	ds_read_b128 v[148:151], v190 offset:16384
	ds_read_b128 v[152:155], v190 offset:17408
	ds_read_b128 v[156:159], v190 offset:18432
	ds_read_b128 v[160:163], v190 offset:19456
	ds_read_b128 v[174:177], v190 offset:20480
	ds_read_b128 v[178:181], v190 offset:21504
	ds_read_b128 v[182:185], v190 offset:22528
	ds_read_b128 v[192:195], v190 offset:23552
	global_load_lds_dwordx4 v[216:217], off
	v_lshl_add_u64 v[218:219], s[24:25], 0, v[166:167]
	s_mov_b32 m0, s35
	s_nop 0
	global_load_lds_dwordx4 v[218:219], off
	s_waitcnt vmcnt(10)
	s_setprio 1
	s_barrier
	s_waitcnt lgkmcnt(0)
	v_mfma_f32_16x16x32_bf16 v[64:67], v[132:135], v[148:151], v[64:67]
	v_mfma_f32_16x16x32_bf16 v[64:67], v[136:139], v[152:155], v[64:67]
	v_mfma_f32_16x16x32_bf16 v[56:59], v[136:139], v[160:163], v[56:59]
	v_mfma_f32_16x16x32_bf16 v[56:59], v[132:135], v[156:159], v[56:59]
	v_mfma_f32_16x16x32_bf16 v[32:35], v[132:135], v[174:177], v[32:35]
	v_mfma_f32_16x16x32_bf16 v[32:35], v[136:139], v[178:181], v[32:35]
	v_mfma_f32_16x16x32_bf16 v[24:27], v[136:139], v[192:195], v[24:27]
	v_mfma_f32_16x16x32_bf16 v[24:27], v[132:135], v[182:185], v[24:27]
	v_mfma_f32_16x16x32_bf16 v[20:23], v[140:143], v[182:185], v[20:23]
	v_mfma_f32_16x16x32_bf16 v[20:23], v[144:147], v[192:195], v[20:23]
	v_mfma_f32_16x16x32_bf16 v[28:31], v[144:147], v[178:181], v[28:31]
	v_mfma_f32_16x16x32_bf16 v[28:31], v[140:143], v[174:177], v[28:31]
	v_mfma_f32_16x16x32_bf16 v[52:55], v[140:143], v[156:159], v[52:55]
	v_mfma_f32_16x16x32_bf16 v[52:55], v[144:147], v[160:163], v[52:55]
	v_mfma_f32_16x16x32_bf16 v[60:63], v[144:147], v[152:155], v[60:63]
	v_mfma_f32_16x16x32_bf16 v[60:63], v[140:143], v[148:151], v[60:63]
	s_barrier
	s_setprio 0
	s_add_u32 s50, s22, 0x80000
	s_addc_u32 s51, s23, 0
	s_add_i32 s49, s52, s31
	v_lshl_add_u64 v[132:133], s[50:51], 0, v[2:3]
	s_mov_b32 m0, s49
	s_nop 0
	global_load_lds_dwordx4 v[132:133], off
	v_lshl_add_u64 v[132:133], s[50:51], 0, v[164:165]
	s_add_i32 m0, s49, 0x2000
	s_nop 0
	global_load_lds_dwordx4 v[132:133], off
	s_add_i32 s49, 0, 0x18000
	v_add_u32_e32 v144, s49, v188
	ds_read_b128 v[132:135], v144
	ds_read_b128 v[136:139], v144 offset:1024
	ds_read_b128 v[140:143], v144 offset:2048
	ds_read_b128 v[144:147], v144 offset:3072
	s_waitcnt vmcnt(6)
	s_setprio 1
	s_barrier
	v_mfma_f32_16x16x32_bf16 v[48:51], v[200:203], v[148:151], v[48:51]
	v_mfma_f32_16x16x32_bf16 v[48:51], v[204:207], v[152:155], v[48:51]
	v_mfma_f32_16x16x32_bf16 v[40:43], v[204:207], v[160:163], v[40:43]
	v_mfma_f32_16x16x32_bf16 v[40:43], v[200:203], v[156:159], v[40:43]
	v_mfma_f32_16x16x32_bf16 v[16:19], v[200:203], v[174:177], v[16:19]
	v_mfma_f32_16x16x32_bf16 v[16:19], v[204:207], v[178:181], v[16:19]
	v_mfma_f32_16x16x32_bf16 v[8:11], v[204:207], v[192:195], v[8:11]
	v_mfma_f32_16x16x32_bf16 v[8:11], v[200:203], v[182:185], v[8:11]
	v_mfma_f32_16x16x32_bf16 v[4:7], v[208:211], v[182:185], v[4:7]
	v_mfma_f32_16x16x32_bf16 v[4:7], v[212:215], v[192:195], v[4:7]
	v_mfma_f32_16x16x32_bf16 v[12:15], v[212:215], v[178:181], v[12:15]
	v_mfma_f32_16x16x32_bf16 v[12:15], v[208:211], v[174:177], v[12:15]
	v_mfma_f32_16x16x32_bf16 v[36:39], v[208:211], v[156:159], v[36:39]
	v_mfma_f32_16x16x32_bf16 v[36:39], v[212:215], v[160:163], v[36:39]
	v_mfma_f32_16x16x32_bf16 v[44:47], v[212:215], v[152:155], v[44:47]
	v_mfma_f32_16x16x32_bf16 v[44:47], v[208:211], v[148:151], v[44:47]
	s_barrier
	s_setprio 0
	s_add_u32 s24, s24, 0x80000
	s_addc_u32 s25, s25, 0
	s_mov_b32 m0, s36
	v_lshl_add_u64 v[200:201], s[24:25], 0, v[168:169]
	ds_read_b128 v[148:151], v190 offset:32768
	ds_read_b128 v[152:155], v190 offset:33792
	ds_read_b128 v[156:159], v190 offset:34816
	ds_read_b128 v[160:163], v190 offset:35840
	ds_read_b128 v[174:177], v190 offset:36864
	ds_read_b128 v[178:181], v190 offset:37888
	ds_read_b128 v[182:185], v190 offset:38912
	ds_read_b128 v[192:195], v190 offset:39936
	global_load_lds_dwordx4 v[200:201], off
	v_lshl_add_u64 v[200:201], s[24:25], 0, v[166:167]
	s_mov_b32 m0, s37
	s_nop 0
	global_load_lds_dwordx4 v[200:201], off
	s_waitcnt lgkmcnt(8)
	s_setprio 1
	s_barrier
	s_waitcnt lgkmcnt(0)
	v_mfma_f32_16x16x32_bf16 v[128:131], v[132:135], v[148:151], v[128:131]
	v_mfma_f32_16x16x32_bf16 v[128:131], v[136:139], v[152:155], v[128:131]
	v_mfma_f32_16x16x32_bf16 v[120:123], v[136:139], v[160:163], v[120:123]
	v_mfma_f32_16x16x32_bf16 v[120:123], v[132:135], v[156:159], v[120:123]
	v_mfma_f32_16x16x32_bf16 v[96:99], v[132:135], v[174:177], v[96:99]
	v_mfma_f32_16x16x32_bf16 v[96:99], v[136:139], v[178:181], v[96:99]
	v_mfma_f32_16x16x32_bf16 v[88:91], v[136:139], v[192:195], v[88:91]
	v_mfma_f32_16x16x32_bf16 v[88:91], v[132:135], v[182:185], v[88:91]
	v_mfma_f32_16x16x32_bf16 v[84:87], v[140:143], v[182:185], v[84:87]
	v_mfma_f32_16x16x32_bf16 v[84:87], v[144:147], v[192:195], v[84:87]
	v_mfma_f32_16x16x32_bf16 v[92:95], v[144:147], v[178:181], v[92:95]
	v_mfma_f32_16x16x32_bf16 v[92:95], v[140:143], v[174:177], v[92:95]
	v_mfma_f32_16x16x32_bf16 v[116:119], v[140:143], v[156:159], v[116:119]
	v_mfma_f32_16x16x32_bf16 v[116:119], v[144:147], v[160:163], v[116:119]
	v_mfma_f32_16x16x32_bf16 v[124:127], v[144:147], v[152:155], v[124:127]
	v_mfma_f32_16x16x32_bf16 v[124:127], v[140:143], v[148:151], v[124:127]
	s_barrier
	s_setprio 0
	s_add_i32 s24, 0, 0x1c000
	s_add_i32 s25, s49, s31
	v_add_u32_e32 v191, s24, v188
	v_lshl_add_u64 v[186:187], v[186:187], 0, s[2:3]
	s_mov_b32 m0, s25
	ds_read_b128 v[200:203], v191
	ds_read_b128 v[204:207], v191 offset:1024
	ds_read_b128 v[208:211], v191 offset:2048
	ds_read_b128 v[212:215], v191 offset:3072
	global_load_lds_dwordx4 v[186:187], off
	v_lshl_add_u64 v[186:187], v[196:197], 0, s[2:3]
	s_add_i32 m0, s25, 0x2000
	s_nop 0
	global_load_lds_dwordx4 v[186:187], off
	s_setprio 1
	s_barrier
	s_waitcnt lgkmcnt(0)
	v_mfma_f32_16x16x32_bf16 v[112:115], v[200:203], v[148:151], v[112:115]
	v_mfma_f32_16x16x32_bf16 v[112:115], v[204:207], v[152:155], v[112:115]
	v_mfma_f32_16x16x32_bf16 v[104:107], v[204:207], v[160:163], v[104:107]
	v_mfma_f32_16x16x32_bf16 v[104:107], v[200:203], v[156:159], v[104:107]
	v_mfma_f32_16x16x32_bf16 v[80:83], v[200:203], v[174:177], v[80:83]
	v_mfma_f32_16x16x32_bf16 v[80:83], v[204:207], v[178:181], v[80:83]
	v_mfma_f32_16x16x32_bf16 v[72:75], v[204:207], v[192:195], v[72:75]
	v_mfma_f32_16x16x32_bf16 v[72:75], v[200:203], v[182:185], v[72:75]
	v_mfma_f32_16x16x32_bf16 v[68:71], v[208:211], v[182:185], v[68:71]
	v_mfma_f32_16x16x32_bf16 v[68:71], v[212:215], v[192:195], v[68:71]
	v_mfma_f32_16x16x32_bf16 v[76:79], v[212:215], v[178:181], v[76:79]
	v_mfma_f32_16x16x32_bf16 v[76:79], v[208:211], v[174:177], v[76:79]
	v_mfma_f32_16x16x32_bf16 v[100:103], v[208:211], v[156:159], v[100:103]
	v_mfma_f32_16x16x32_bf16 v[100:103], v[212:215], v[160:163], v[100:103]
	v_mfma_f32_16x16x32_bf16 v[108:111], v[212:215], v[152:155], v[108:111]
	v_mfma_f32_16x16x32_bf16 v[108:111], v[208:211], v[148:151], v[108:111]
	s_barrier
	s_setprio 0
	s_mov_b32 m0, s41
	v_lshl_add_u64 v[186:187], v[216:217], 0, s[2:3]
	ds_read_b128 v[148:151], v190 offset:49152
	ds_read_b128 v[152:155], v190 offset:50176
	ds_read_b128 v[156:159], v190 offset:51200
	ds_read_b128 v[160:163], v190 offset:52224
	ds_read_b128 v[174:177], v190 offset:53248
	ds_read_b128 v[178:181], v190 offset:54272
	ds_read_b128 v[182:185], v190 offset:55296
	ds_read_b128 v[192:195], v190 offset:56320
	global_load_lds_dwordx4 v[186:187], off
	v_lshl_add_u64 v[186:187], v[218:219], 0, s[2:3]
	s_mov_b32 m0, s42
	s_nop 0
	global_load_lds_dwordx4 v[186:187], off
	s_setprio 1
	s_barrier
	s_waitcnt lgkmcnt(0)
	v_mfma_f32_16x16x32_bf16 v[64:67], v[132:135], v[148:151], v[64:67]
	v_mfma_f32_16x16x32_bf16 v[64:67], v[136:139], v[152:155], v[64:67]
	v_mfma_f32_16x16x32_bf16 v[56:59], v[136:139], v[160:163], v[56:59]
	v_mfma_f32_16x16x32_bf16 v[56:59], v[132:135], v[156:159], v[56:59]
	v_mfma_f32_16x16x32_bf16 v[32:35], v[132:135], v[174:177], v[32:35]
	v_mfma_f32_16x16x32_bf16 v[32:35], v[136:139], v[178:181], v[32:35]
	v_mfma_f32_16x16x32_bf16 v[24:27], v[136:139], v[192:195], v[24:27]
	v_mfma_f32_16x16x32_bf16 v[24:27], v[132:135], v[182:185], v[24:27]
	v_mfma_f32_16x16x32_bf16 v[20:23], v[140:143], v[182:185], v[20:23]
	v_mfma_f32_16x16x32_bf16 v[20:23], v[144:147], v[192:195], v[20:23]
	v_mfma_f32_16x16x32_bf16 v[28:31], v[144:147], v[178:181], v[28:31]
	v_mfma_f32_16x16x32_bf16 v[28:31], v[140:143], v[174:177], v[28:31]
	v_mfma_f32_16x16x32_bf16 v[52:55], v[140:143], v[156:159], v[52:55]
	v_mfma_f32_16x16x32_bf16 v[52:55], v[144:147], v[160:163], v[52:55]
	v_mfma_f32_16x16x32_bf16 v[60:63], v[144:147], v[152:155], v[60:63]
	v_mfma_f32_16x16x32_bf16 v[60:63], v[140:143], v[148:151], v[60:63]
	s_barrier
	s_setprio 0
	s_add_u32 s22, s22, 0x80080
	s_addc_u32 s23, s23, 0
	s_add_i32 s24, s24, s31
	v_lshl_add_u64 v[132:133], s[22:23], 0, v[2:3]
	s_mov_b32 m0, s24
	s_nop 0
	global_load_lds_dwordx4 v[132:133], off
	v_lshl_add_u64 v[132:133], s[22:23], 0, v[164:165]
	s_add_i32 m0, s24, 0x2000
	s_nop 0
	global_load_lds_dwordx4 v[132:133], off
	s_waitcnt vmcnt(6)
	s_setprio 1
	s_barrier
	v_mfma_f32_16x16x32_bf16 v[48:51], v[200:203], v[148:151], v[48:51]
	v_mfma_f32_16x16x32_bf16 v[48:51], v[204:207], v[152:155], v[48:51]
	v_mfma_f32_16x16x32_bf16 v[40:43], v[204:207], v[160:163], v[40:43]
	v_mfma_f32_16x16x32_bf16 v[40:43], v[200:203], v[156:159], v[40:43]
	v_mfma_f32_16x16x32_bf16 v[16:19], v[200:203], v[174:177], v[16:19]
	v_mfma_f32_16x16x32_bf16 v[16:19], v[204:207], v[178:181], v[16:19]
	v_mfma_f32_16x16x32_bf16 v[8:11], v[204:207], v[192:195], v[8:11]
	v_mfma_f32_16x16x32_bf16 v[8:11], v[200:203], v[182:185], v[8:11]
	v_mfma_f32_16x16x32_bf16 v[4:7], v[208:211], v[182:185], v[4:7]
	v_mfma_f32_16x16x32_bf16 v[4:7], v[212:215], v[192:195], v[4:7]
	v_mfma_f32_16x16x32_bf16 v[12:15], v[212:215], v[178:181], v[12:15]
	v_mfma_f32_16x16x32_bf16 v[12:15], v[208:211], v[174:177], v[12:15]
	v_mfma_f32_16x16x32_bf16 v[36:39], v[208:211], v[156:159], v[36:39]
	v_mfma_f32_16x16x32_bf16 v[36:39], v[212:215], v[160:163], v[36:39]
	v_mfma_f32_16x16x32_bf16 v[44:47], v[212:215], v[152:155], v[44:47]
	v_mfma_f32_16x16x32_bf16 v[44:47], v[208:211], v[148:151], v[44:47]
	s_barrier
	s_setprio 0
	s_add_i32 s48, s48, 2
	s_add_u32 s20, s20, 0x100
	s_addc_u32 s21, s21, 0
	s_add_u32 s46, s46, 0x100
	s_addc_u32 s47, s47, 0
	s_cmp_gt_u32 s48, 29
	s_cbranch_scc0 .LBB0_878
	s_cmp_lt_i32 s43, 32
	s_mov_b64 s[20:21], 0
	s_cbranch_scc1 .LBB0_881
	s_sub_i32 s13, s43, 32
	s_lshr_b32 s13, s13, 4
	s_add_i32 s13, s13, 1
	s_mul_hi_u32 s21, s13, 0x3000
	s_mul_i32 s20, s13, 0x3000

.LBB0_1002:
	s_add_u32 s28, s26, 0x100
	s_addc_u32 s29, s27, 0
	s_add_i32 s58, 0, 0x10000
	v_add_u32_e32 v56, s58, v1
	ds_read_b128 v[44:47], v56
	ds_read_b128 v[48:51], v56 offset:1024
	ds_read_b128 v[52:55], v56 offset:2048
	ds_read_b128 v[56:59], v56 offset:3072
	s_cmp_eq_u32 s57, 28
	s_cselect_b32 s35, s21, s29
	s_cselect_b32 s34, s53, s28
	s_cselect_b32 s31, s19, s56
	s_cselect_b32 s30, s54, s55
	v_lshl_add_u64 v[190:191], s[26:27], 0, v[178:179]
	s_add_i32 m0, s42, 0xc000
	ds_read_b128 v[68:71], v200
	ds_read_b128 v[72:75], v200 offset:1024
	ds_read_b128 v[76:79], v200 offset:2048
	ds_read_b128 v[80:83], v200 offset:3072
	ds_read_b128 v[164:167], v200 offset:4096
	ds_read_b128 v[168:171], v200 offset:5120
	ds_read_b128 v[182:185], v200 offset:6144
	ds_read_b128 v[186:189], v200 offset:7168
	global_load_lds_dwordx4 v[190:191], off
	v_lshl_add_u64 v[190:191], s[26:27], 0, v[180:181]
	s_add_i32 m0, s42, 0xe000
	s_nop 0
	global_load_lds_dwordx4 v[190:191], off
	s_waitcnt lgkmcnt(8)
	s_setprio 1
	s_barrier
	s_waitcnt lgkmcnt(0)
	v_mfma_f32_16x16x32_bf16 v[160:163], v[44:47], v[68:71], v[160:163]
	v_mfma_f32_16x16x32_bf16 v[160:163], v[48:51], v[72:75], v[160:163]
	v_mfma_f32_16x16x32_bf16 v[148:151], v[48:51], v[80:83], v[148:151]
	v_mfma_f32_16x16x32_bf16 v[148:151], v[44:47], v[76:79], v[148:151]
	v_mfma_f32_16x16x32_bf16 v[132:135], v[44:47], v[164:167], v[132:135]
	v_mfma_f32_16x16x32_bf16 v[132:135], v[48:51], v[168:171], v[132:135]
	v_mfma_f32_16x16x32_bf16 v[116:119], v[48:51], v[186:189], v[116:119]
	v_mfma_f32_16x16x32_bf16 v[116:119], v[44:47], v[182:185], v[116:119]
	v_mfma_f32_16x16x32_bf16 v[108:111], v[52:55], v[182:185], v[108:111]
	v_mfma_f32_16x16x32_bf16 v[108:111], v[56:59], v[186:189], v[108:111]
	v_mfma_f32_16x16x32_bf16 v[124:127], v[56:59], v[168:171], v[124:127]
	v_mfma_f32_16x16x32_bf16 v[124:127], v[52:55], v[164:167], v[124:127]
	v_mfma_f32_16x16x32_bf16 v[140:143], v[52:55], v[76:79], v[140:143]
	v_mfma_f32_16x16x32_bf16 v[140:143], v[56:59], v[80:83], v[140:143]
	v_mfma_f32_16x16x32_bf16 v[156:159], v[56:59], v[72:75], v[156:159]
	v_mfma_f32_16x16x32_bf16 v[156:159], v[52:55], v[68:71], v[156:159]
	s_barrier
	s_setprio 0
	s_add_i32 s59, 0, 0x14000
	v_add_u32_e32 v194, s59, v1
	s_add_i32 s26, s58, s41
	ds_read_b128 v[190:193], v194
	ds_read_b128 v[202:205], v194 offset:1024
	ds_read_b128 v[206:209], v194 offset:2048
	ds_read_b128 v[210:213], v194 offset:3072
	v_lshl_add_u64 v[194:195], s[30:31], 0, v[2:3]
	s_mov_b32 m0, s26
	v_lshl_add_u64 v[222:223], s[30:31], 0, v[172:173]
	global_load_lds_dwordx4 v[194:195], off
	s_add_i32 m0, s26, 0x2000
	s_nop 0
	global_load_lds_dwordx4 v[222:223], off
	s_setprio 1
	s_barrier
	s_waitcnt lgkmcnt(0)
	v_mfma_f32_16x16x32_bf16 v[152:155], v[190:193], v[68:71], v[152:155]
	v_mfma_f32_16x16x32_bf16 v[152:155], v[202:205], v[72:75], v[152:155]
	v_mfma_f32_16x16x32_bf16 v[68:71], v[206:209], v[68:71], v[144:147]
	v_mfma_f32_16x16x32_bf16 v[68:71], v[210:213], v[72:75], v[68:71]
	v_mfma_f32_16x16x32_bf16 v[72:75], v[190:193], v[76:79], v[136:139]
	v_mfma_f32_16x16x32_bf16 v[72:75], v[202:205], v[80:83], v[72:75]
	v_mfma_f32_16x16x32_bf16 v[76:79], v[206:209], v[76:79], v[128:131]
	v_mfma_f32_16x16x32_bf16 v[76:79], v[210:213], v[80:83], v[76:79]
	v_mfma_f32_16x16x32_bf16 v[112:115], v[206:209], v[164:167], v[112:115]
	v_mfma_f32_16x16x32_bf16 v[112:115], v[210:213], v[168:171], v[112:115]
	v_mfma_f32_16x16x32_bf16 v[104:107], v[190:193], v[182:185], v[104:107]
	v_mfma_f32_16x16x32_bf16 v[104:107], v[202:205], v[186:189], v[104:107]
	v_mfma_f32_16x16x32_bf16 v[96:99], v[206:209], v[182:185], v[96:99]
	v_mfma_f32_16x16x32_bf16 v[96:99], v[210:213], v[186:189], v[96:99]
	v_mfma_f32_16x16x32_bf16 v[80:83], v[190:193], v[164:167], v[120:123]
	v_mfma_f32_16x16x32_bf16 v[80:83], v[202:205], v[168:171], v[80:83]
	s_barrier
	s_setprio 0
	s_mov_b32 m0, s42
	v_lshl_add_u64 v[224:225], s[34:35], 0, v[176:177]
	ds_read_b128 v[120:123], v200 offset:16384
	ds_read_b128 v[128:131], v200 offset:17408
	ds_read_b128 v[136:139], v200 offset:18432
	ds_read_b128 v[144:147], v200 offset:19456
	ds_read_b128 v[164:167], v200 offset:20480
	ds_read_b128 v[168:171], v200 offset:21504
	ds_read_b128 v[182:185], v200 offset:22528
	ds_read_b128 v[186:189], v200 offset:23552
	global_load_lds_dwordx4 v[224:225], off
	v_lshl_add_u64 v[226:227], s[34:35], 0, v[174:175]
	s_mov_b32 m0, s43
	s_nop 0
	global_load_lds_dwordx4 v[226:227], off
	s_waitcnt vmcnt(10)
	s_setprio 1
	s_barrier
	s_waitcnt lgkmcnt(0)
	v_mfma_f32_16x16x32_bf16 v[100:103], v[44:47], v[120:123], v[100:103]
	v_mfma_f32_16x16x32_bf16 v[100:103], v[48:51], v[128:131], v[100:103]
	v_mfma_f32_16x16x32_bf16 v[84:87], v[48:51], v[144:147], v[84:87]
	v_mfma_f32_16x16x32_bf16 v[84:87], v[44:47], v[136:139], v[84:87]
	v_mfma_f32_16x16x32_bf16 v[36:39], v[44:47], v[164:167], v[36:39]
	v_mfma_f32_16x16x32_bf16 v[36:39], v[48:51], v[168:171], v[36:39]
	v_mfma_f32_16x16x32_bf16 v[16:19], v[48:51], v[186:189], v[16:19]
	v_mfma_f32_16x16x32_bf16 v[16:19], v[44:47], v[182:185], v[16:19]
	v_mfma_f32_16x16x32_bf16 v[12:15], v[52:55], v[182:185], v[12:15]
	v_mfma_f32_16x16x32_bf16 v[12:15], v[56:59], v[186:189], v[12:15]
	v_mfma_f32_16x16x32_bf16 v[28:31], v[56:59], v[168:171], v[28:31]
	v_mfma_f32_16x16x32_bf16 v[28:31], v[52:55], v[164:167], v[28:31]
	v_mfma_f32_16x16x32_bf16 v[60:63], v[52:55], v[136:139], v[60:63]
	v_mfma_f32_16x16x32_bf16 v[60:63], v[56:59], v[144:147], v[60:63]
	v_mfma_f32_16x16x32_bf16 v[92:95], v[56:59], v[128:131], v[92:95]
	v_mfma_f32_16x16x32_bf16 v[92:95], v[52:55], v[120:123], v[92:95]
	s_barrier
	s_setprio 0
	s_add_u32 s26, s30, 0x80000
	s_addc_u32 s27, s31, 0
	s_add_i32 s58, s59, s41
	v_lshl_add_u64 v[44:45], s[26:27], 0, v[2:3]
	s_mov_b32 m0, s58
	s_nop 0
	global_load_lds_dwordx4 v[44:45], off
	v_lshl_add_u64 v[44:45], s[26:27], 0, v[172:173]
	s_add_i32 m0, s58, 0x2000
	s_nop 0
	global_load_lds_dwordx4 v[44:45], off
	s_add_i32 s58, 0, 0x18000
	v_add_u32_e32 v44, s58, v1
	ds_read_b128 v[52:55], v44
	ds_read_b128 v[56:59], v44 offset:1024
	s_waitcnt vmcnt(6)
	s_setprio 1
	s_barrier
	v_mfma_f32_16x16x32_bf16 v[40:43], v[190:193], v[136:139], v[40:43]
	v_mfma_f32_16x16x32_bf16 v[40:43], v[202:205], v[144:147], v[40:43]
	v_mfma_f32_16x16x32_bf16 v[24:27], v[202:205], v[168:171], v[24:27]
	v_mfma_f32_16x16x32_bf16 v[24:27], v[190:193], v[164:167], v[24:27]
	v_mfma_f32_16x16x32_bf16 v[8:11], v[190:193], v[182:185], v[8:11]
	v_mfma_f32_16x16x32_bf16 v[8:11], v[202:205], v[186:189], v[8:11]
	v_mfma_f32_16x16x32_bf16 v[44:47], v[202:205], v[128:131], v[88:91]
	v_mfma_f32_16x16x32_bf16 v[44:47], v[190:193], v[120:123], v[44:47]
	v_mfma_f32_16x16x32_bf16 v[48:51], v[206:209], v[120:123], v[64:67]
	v_mfma_f32_16x16x32_bf16 v[48:51], v[210:213], v[128:131], v[48:51]
	v_mfma_f32_16x16x32_bf16 v[4:7], v[210:213], v[186:189], v[4:7]
	v_mfma_f32_16x16x32_bf16 v[4:7], v[206:209], v[182:185], v[4:7]
	v_mfma_f32_16x16x32_bf16 v[20:23], v[206:209], v[164:167], v[20:23]
	v_mfma_f32_16x16x32_bf16 v[20:23], v[210:213], v[168:171], v[20:23]
	v_mfma_f32_16x16x32_bf16 v[32:35], v[210:213], v[144:147], v[32:35]
	v_mfma_f32_16x16x32_bf16 v[32:35], v[206:209], v[136:139], v[32:35]
	s_barrier
	s_setprio 0
	v_add_u32_e32 v88, s58, v1
	ds_read_b128 v[64:67], v88 offset:2048
	ds_read_b128 v[88:91], v88 offset:3072
	s_add_u32 s26, s34, 0x4000
	s_addc_u32 s27, s35, 0
	s_mov_b32 m0, s44
	v_lshl_add_u64 v[136:137], s[26:27], 0, v[176:177]
	ds_read_b128 v[120:123], v200 offset:32768
	ds_read_b128 v[128:131], v200 offset:33792
	ds_read_b128 v[164:167], v200 offset:34816
	ds_read_b128 v[168:171], v200 offset:35840
	ds_read_b128 v[182:185], v200 offset:36864
	ds_read_b128 v[186:189], v200 offset:37888
	ds_read_b128 v[190:193], v200 offset:38912
	ds_read_b128 v[202:205], v200 offset:39936
	global_load_lds_dwordx4 v[136:137], off
	v_lshl_add_u64 v[136:137], s[26:27], 0, v[174:175]
	s_mov_b32 m0, s45
	s_nop 0
	global_load_lds_dwordx4 v[136:137], off
	s_waitcnt lgkmcnt(8)
	s_setprio 1
	s_barrier
	s_waitcnt lgkmcnt(0)
	v_mfma_f32_16x16x32_bf16 v[136:139], v[52:55], v[120:123], v[160:163]
	v_mfma_f32_16x16x32_bf16 v[160:163], v[56:59], v[128:131], v[136:139]
	v_mfma_f32_16x16x32_bf16 v[136:139], v[64:67], v[120:123], v[156:159]
	v_mfma_f32_16x16x32_bf16 v[156:159], v[88:91], v[128:131], v[136:139]
	v_mfma_f32_16x16x32_bf16 v[136:139], v[52:55], v[164:167], v[148:151]
	v_mfma_f32_16x16x32_bf16 v[148:151], v[56:59], v[168:171], v[136:139]
	v_mfma_f32_16x16x32_bf16 v[136:139], v[64:67], v[164:167], v[140:143]
	v_mfma_f32_16x16x32_bf16 v[140:143], v[88:91], v[168:171], v[136:139]
	v_mfma_f32_16x16x32_bf16 v[132:135], v[52:55], v[182:185], v[132:135]
	v_mfma_f32_16x16x32_bf16 v[132:135], v[56:59], v[186:189], v[132:135]
	v_mfma_f32_16x16x32_bf16 v[124:127], v[64:67], v[182:185], v[124:127]
	v_mfma_f32_16x16x32_bf16 v[124:127], v[88:91], v[186:189], v[124:127]
	v_mfma_f32_16x16x32_bf16 v[116:119], v[52:55], v[190:193], v[116:119]
	v_mfma_f32_16x16x32_bf16 v[116:119], v[56:59], v[202:205], v[116:119]
	v_mfma_f32_16x16x32_bf16 v[108:111], v[64:67], v[190:193], v[108:111]
	v_mfma_f32_16x16x32_bf16 v[108:111], v[88:91], v[202:205], v[108:111]
	s_barrier
	s_setprio 0
	s_add_i32 s34, 0, 0x1c000
	v_add_u32_e32 v136, s34, v1
	s_add_i32 s26, s58, s41
	ds_read_b128 v[206:209], v136
	ds_read_b128 v[210:213], v136 offset:1024
	ds_read_b128 v[214:217], v136 offset:2048
	ds_read_b128 v[218:221], v136 offset:3072
	v_lshl_add_u64 v[136:137], v[194:195], 0, s[2:3]
	s_mov_b32 m0, s26
	s_nop 0
	global_load_lds_dwordx4 v[136:137], off
	v_lshl_add_u64 v[136:137], v[222:223], 0, s[2:3]
	s_add_i32 m0, s26, 0x2000
	s_nop 0
	global_load_lds_dwordx4 v[136:137], off
	s_setprio 1
	s_barrier
	s_waitcnt lgkmcnt(0)
	v_mfma_f32_16x16x32_bf16 v[68:71], v[214:217], v[120:123], v[68:71]
	v_mfma_f32_16x16x32_bf16 v[144:147], v[218:221], v[128:131], v[68:71]
	v_mfma_f32_16x16x32_bf16 v[136:139], v[206:209], v[120:123], v[152:155]
	v_mfma_f32_16x16x32_bf16 v[152:155], v[210:213], v[128:131], v[136:139]
	v_mfma_f32_16x16x32_bf16 v[68:71], v[206:209], v[164:167], v[72:75]
	v_mfma_f32_16x16x32_bf16 v[136:139], v[210:213], v[168:171], v[68:71]
	v_mfma_f32_16x16x32_bf16 v[68:71], v[214:217], v[164:167], v[76:79]
	v_mfma_f32_16x16x32_bf16 v[128:131], v[218:221], v[168:171], v[68:71]
	v_mfma_f32_16x16x32_bf16 v[68:71], v[206:209], v[182:185], v[80:83]
	v_mfma_f32_16x16x32_bf16 v[120:123], v[210:213], v[186:189], v[68:71]
	v_mfma_f32_16x16x32_bf16 v[68:71], v[214:217], v[182:185], v[112:115]
	v_mfma_f32_16x16x32_bf16 v[112:115], v[218:221], v[186:189], v[68:71]
	v_mfma_f32_16x16x32_bf16 v[68:71], v[206:209], v[190:193], v[104:107]
	v_mfma_f32_16x16x32_bf16 v[104:107], v[210:213], v[202:205], v[68:71]
	v_mfma_f32_16x16x32_bf16 v[68:71], v[214:217], v[190:193], v[96:99]
	v_mfma_f32_16x16x32_bf16 v[96:99], v[218:221], v[202:205], v[68:71]
	s_barrier
	s_setprio 0
	s_mov_b32 m0, s48
	v_lshl_add_u64 v[190:191], v[224:225], 0, s[2:3]
	s_nop 2
	ds_read_b128 v[68:71], v200 offset:49152
	ds_read_b128 v[72:75], v200 offset:50176
	ds_read_b128 v[76:79], v200 offset:51200
	ds_read_b128 v[80:83], v200 offset:52224
	ds_read_b128 v[164:167], v200 offset:53248
	ds_read_b128 v[168:171], v200 offset:54272
	ds_read_b128 v[182:185], v200 offset:55296
	ds_read_b128 v[186:189], v200 offset:56320
	global_load_lds_dwordx4 v[190:191], off
	v_lshl_add_u64 v[190:191], v[226:227], 0, s[2:3]
	s_mov_b32 m0, s49
	s_nop 0
	global_load_lds_dwordx4 v[190:191], off
	s_setprio 1
	s_barrier
	s_waitcnt lgkmcnt(0)
	v_mfma_f32_16x16x32_bf16 v[100:103], v[52:55], v[68:71], v[100:103]
	v_mfma_f32_16x16x32_bf16 v[100:103], v[56:59], v[72:75], v[100:103]
	v_mfma_f32_16x16x32_bf16 v[84:87], v[56:59], v[80:83], v[84:87]
	v_mfma_f32_16x16x32_bf16 v[84:87], v[52:55], v[76:79], v[84:87]
	v_mfma_f32_16x16x32_bf16 v[36:39], v[52:55], v[164:167], v[36:39]
	v_mfma_f32_16x16x32_bf16 v[36:39], v[56:59], v[168:171], v[36:39]
	v_mfma_f32_16x16x32_bf16 v[16:19], v[56:59], v[186:189], v[16:19]
	v_mfma_f32_16x16x32_bf16 v[16:19], v[52:55], v[182:185], v[16:19]
	v_mfma_f32_16x16x32_bf16 v[12:15], v[64:67], v[182:185], v[12:15]
	v_mfma_f32_16x16x32_bf16 v[12:15], v[88:91], v[186:189], v[12:15]
	v_mfma_f32_16x16x32_bf16 v[28:31], v[88:91], v[168:171], v[28:31]
	v_mfma_f32_16x16x32_bf16 v[28:31], v[64:67], v[164:167], v[28:31]
	v_mfma_f32_16x16x32_bf16 v[60:63], v[64:67], v[76:79], v[60:63]
	v_mfma_f32_16x16x32_bf16 v[60:63], v[88:91], v[80:83], v[60:63]
	v_mfma_f32_16x16x32_bf16 v[92:95], v[88:91], v[72:75], v[92:95]
	v_mfma_f32_16x16x32_bf16 v[92:95], v[64:67], v[68:71], v[92:95]
	s_barrier
	s_setprio 0
	s_add_u32 s26, s30, 0x80080
	s_addc_u32 s27, s31, 0
	s_add_i32 s30, s34, s41
	s_mov_b32 m0, s30
	s_nop 0
	global_load_lds_dwordx4 v2, s[26:27]
	s_add_i32 m0, s30, 0x2000
	s_nop 0
	global_load_lds_dwordx4 v172, s[26:27]
	s_waitcnt vmcnt(6)
	s_setprio 1
	s_barrier
	v_mfma_f32_16x16x32_bf16 v[44:47], v[206:209], v[68:71], v[44:47]
	v_mfma_f32_16x16x32_bf16 v[88:91], v[210:213], v[72:75], v[44:47]
	v_mfma_f32_16x16x32_bf16 v[44:47], v[214:217], v[68:71], v[48:51]
	v_mfma_f32_16x16x32_bf16 v[64:67], v[218:221], v[72:75], v[44:47]
	v_mfma_f32_16x16x32_bf16 v[40:43], v[206:209], v[76:79], v[40:43]
	v_mfma_f32_16x16x32_bf16 v[40:43], v[210:213], v[80:83], v[40:43]
	v_mfma_f32_16x16x32_bf16 v[32:35], v[214:217], v[76:79], v[32:35]
	v_mfma_f32_16x16x32_bf16 v[32:35], v[218:221], v[80:83], v[32:35]
	v_mfma_f32_16x16x32_bf16 v[24:27], v[206:209], v[164:167], v[24:27]
	v_mfma_f32_16x16x32_bf16 v[24:27], v[210:213], v[168:171], v[24:27]
	v_mfma_f32_16x16x32_bf16 v[20:23], v[214:217], v[164:167], v[20:23]
	v_mfma_f32_16x16x32_bf16 v[20:23], v[218:221], v[168:171], v[20:23]
	v_mfma_f32_16x16x32_bf16 v[8:11], v[206:209], v[182:185], v[8:11]
	v_mfma_f32_16x16x32_bf16 v[8:11], v[210:213], v[186:189], v[8:11]
	v_mfma_f32_16x16x32_bf16 v[4:7], v[214:217], v[182:185], v[4:7]
	v_mfma_f32_16x16x32_bf16 v[4:7], v[218:221], v[186:189], v[4:7]
	s_barrier
	s_setprio 0
	s_add_i32 s57, s57, 2
	s_add_u32 s55, s55, 0x100
	s_addc_u32 s56, s56, 0
	s_cmp_gt_u32 s57, 29
	s_mov_b64 s[26:27], s[28:29]
	s_cbranch_scc0 .LBB0_1002
	v_lshl_or_b32 v182, s52, 7, v197
	v_ashrrev_i32_e32 v183, 31, v182
	v_lshlrev_b64 v[56:57], 2, v[182:183]
	v_lshl_add_u64 v[48:49], s[10:11], 0, v[56:57]
	global_load_dwordx4 v[44:47], v[48:49], off offset:16
	global_load_dwordx4 v[68:71], v[48:49], off
	v_lshl_add_u64 v[52:53], s[14:15], 0, v[56:57]
	global_load_dwordx4 v[48:51], v[52:53], off offset:16
	global_load_dwordx4 v[72:75], v[52:53], off
	v_lshl_add_u64 v[58:59], s[16:17], 0, v[56:57]
	global_load_dwordx4 v[52:55], v[58:59], off offset:16
	global_load_dwordx4 v[76:79], v[58:59], off
	v_lshl_add_u64 v[80:81], s[12:13], 0, v[56:57]
	global_load_dwordx4 v[56:59], v[80:81], off offset:16
	s_nop 0
	global_load_dwordx4 v[80:83], v[80:81], off
	v_mov_b32_dpp v164, v8 row_shr:1 row_mask:0xf bank_mask:0xf bound_ctrl:1
	v_mov_b32_dpp v165, v9 row_shr:1 row_mask:0xf bank_mask:0xf bound_ctrl:1
	v_mov_b32_dpp v166, v10 row_shr:1 row_mask:0xf bank_mask:0xf bound_ctrl:1
	v_mov_b32_dpp v167, v11 row_shr:1 row_mask:0xf bank_mask:0xf bound_ctrl:1
	v_mov_b32_dpp v168, v4 row_shr:1 row_mask:0xf bank_mask:0xf bound_ctrl:1
	v_mov_b32_dpp v169, v5 row_shr:1 row_mask:0xf bank_mask:0xf bound_ctrl:1
	v_mov_b32_dpp v170, v6 row_shr:1 row_mask:0xf bank_mask:0xf bound_ctrl:1
	v_mov_b32_dpp v171, v7 row_shr:1 row_mask:0xf bank_mask:0xf bound_ctrl:1
	v_lshl_add_u32 v201, s33, 8, v196
	s_movk_i32 s21, 0x2c00
	s_lshl_b32 s19, s33, 2
	v_mov_b32_dpp v190, v152 row_shl:1 row_mask:0xf bank_mask:0xf bound_ctrl:1
	v_mov_b32_dpp v191, v153 row_shl:1 row_mask:0xf bank_mask:0xf bound_ctrl:1
	v_mov_b32_dpp v188, v154 row_shl:1 row_mask:0xf bank_mask:0xf bound_ctrl:1
	v_mov_b32_dpp v189, v155 row_shl:1 row_mask:0xf bank_mask:0xf bound_ctrl:1
	v_mov_b32_dpp v186, v144 row_shl:1 row_mask:0xf bank_mask:0xf bound_ctrl:1
	v_mov_b32_dpp v187, v145 row_shl:1 row_mask:0xf bank_mask:0xf bound_ctrl:1
	v_mov_b32_dpp v184, v146 row_shl:1 row_mask:0xf bank_mask:0xf bound_ctrl:1
	v_mov_b32_dpp v185, v147 row_shl:1 row_mask:0xf bank_mask:0xf bound_ctrl:1
	s_add_i32 s19, s19, s50
	s_waitcnt vmcnt(0)
	v_pk_mul_f32 v[168:169], v[44:45], v[168:169]
	v_pk_mul_f32 v[164:165], v[68:69], v[164:165]
	v_pk_mul_f32 v[166:167], v[70:71], v[166:167]
	v_pk_fma_f32 v[164:165], v[152:153], v[72:73], v[164:165]
	v_pk_fma_f32 v[166:167], v[154:155], v[74:75], v[166:167]
	v_pk_fma_f32 v[164:165], v[136:137], v[76:77], v[164:165]
	v_pk_fma_f32 v[166:167], v[138:139], v[78:79], v[166:167]
	v_pk_add_f32 v[164:165], v[80:81], v[164:165]
	v_pk_add_f32 v[166:167], v[82:83], v[166:167]
	v_mul_f32_e32 v192, 0xbfb8aa3b, v164
	v_mul_f32_e32 v193, 0xbfb8aa3b, v165
	v_exp_f32_e32 v192, v192
	v_exp_f32_e32 v193, v193
	v_pk_fma_f32 v[168:169], v[144:145], v[48:49], v[168:169]
	v_pk_mul_f32 v[170:171], v[46:47], v[170:171]
	v_pk_fma_f32 v[168:169], v[128:129], v[52:53], v[168:169]
	v_pk_add_f32 v[192:193], v[192:193], 1.0 op_sel_hi:[1,0]
	v_pk_add_f32 v[168:169], v[56:57], v[168:169]
	v_rcp_f32_e32 v195, v193
	v_pk_fma_f32 v[170:171], v[146:147], v[50:51], v[170:171]
	v_fma_f32 v202, -v193, v195, 1.0
	v_fmac_f32_e32 v195, v202, v195
	v_div_fixup_f32 v193, v195, v193, 1.0
	v_rcp_f32_e32 v195, v192
	v_pk_fma_f32 v[170:171], v[130:131], v[54:55], v[170:171]
	v_fma_f32 v202, -v192, v195, 1.0
	v_fmac_f32_e32 v195, v202, v195
	v_div_fixup_f32 v192, v195, v192, 1.0
	v_mul_f32_e32 v194, 0xbfb8aa3b, v166
	v_mul_f32_e32 v195, 0xbfb8aa3b, v167
	v_exp_f32_e32 v194, v194
	v_exp_f32_e32 v195, v195
	v_pk_add_f32 v[170:171], v[58:59], v[170:171]
	v_pk_mul_f32 v[192:193], v[164:165], v[192:193]
	v_pk_add_f32 v[194:195], v[194:195], 1.0 op_sel_hi:[1,0]
	s_nop 0
	v_rcp_f32_e32 v203, v195
	v_pk_mul_f32 v[192:193], v[160:161], v[192:193]
	v_fma_f32 v204, -v195, v203, 1.0
	v_fmac_f32_e32 v203, v204, v203
	v_div_fixup_f32 v195, v203, v195, 1.0
	v_rcp_f32_e32 v203, v194
	v_cvt_pk_bf16_f32 v192, v192, v193
	v_fma_f32 v204, -v194, v203, 1.0
	v_fmac_f32_e32 v203, v204, v203
	v_div_fixup_f32 v194, v203, v194, 1.0
	v_mul_f32_e32 v202, 0xbfb8aa3b, v168
	v_mul_f32_e32 v203, 0xbfb8aa3b, v169
	v_exp_f32_e32 v202, v202
	v_exp_f32_e32 v203, v203
	v_pk_mul_f32 v[194:195], v[166:167], v[194:195]
	v_pk_add_f32 v[202:203], v[202:203], 1.0 op_sel_hi:[1,0]
	s_nop 0
	v_rcp_f32_e32 v205, v203
	v_pk_mul_f32 v[194:195], v[162:163], v[194:195]
	v_fma_f32 v206, -v203, v205, 1.0
	v_fmac_f32_e32 v205, v206, v205
	v_div_fixup_f32 v203, v205, v203, 1.0
	v_rcp_f32_e32 v205, v202
	v_cvt_pk_bf16_f32 v193, v194, v195
	v_fma_f32 v206, -v202, v205, 1.0
	v_fmac_f32_e32 v205, v206, v205
	v_div_fixup_f32 v202, v205, v202, 1.0
	v_mul_f32_e32 v204, 0xbfb8aa3b, v170
	v_mul_f32_e32 v205, 0xbfb8aa3b, v171
	v_exp_f32_e32 v204, v204
	v_exp_f32_e32 v205, v205
	v_pk_mul_f32 v[202:203], v[168:169], v[202:203]
	v_pk_add_f32 v[204:205], v[204:205], 1.0 op_sel_hi:[1,0]
	s_nop 0
	v_rcp_f32_e32 v207, v205
	v_pk_mul_f32 v[202:203], v[156:157], v[202:203]
	v_fma_f32 v208, -v205, v207, 1.0
	v_fmac_f32_e32 v207, v208, v207
	v_div_fixup_f32 v205, v207, v205, 1.0
	v_rcp_f32_e32 v207, v204
	v_cvt_pk_bf16_f32 v194, v202, v203
	v_mov_b64_e32 v[202:203], s[0:1]
	v_mad_i64_i32 v[202:203], s[26:27], v201, s21, v[202:203]
	v_fma_f32 v208, -v204, v207, 1.0
	v_fmac_f32_e32 v207, v208, v207
	v_div_fixup_f32 v204, v207, v204, 1.0
	v_pk_mul_f32 v[204:205], v[170:171], v[204:205]
	v_lshl_add_u64 v[202:203], v[182:183], 1, v[202:203]
	v_pk_mul_f32 v[204:205], v[158:159], v[204:205]
	s_nop 0
	v_cvt_pk_bf16_f32 v195, v204, v205
	global_store_dwordx4 v[202:203], v[192:195], off
	s_and_saveexec_b64 s[26:27], s[6:7]
	s_cbranch_execz .LBB0_1005
	s_mul_i32 s28, s19, 0x10800
	s_mul_hi_i32 s21, s19, 0x10800
	s_add_u32 s28, s46, s28
	s_addc_u32 s29, s47, s21
	v_lshl_add_u64 v[192:193], v[182:183], 2, s[28:29]
	global_store_dwordx4 v[192:193], v[164:167], off
	global_store_dwordx4 v[192:193], v[168:171], off offset:16
	s_nop 0
	v_add_co_u32_e32 v164, vcc, 0x5000, v192
	s_nop 1
	v_addc_co_u32_e32 v165, vcc, 0, v193, vcc
	global_store_dwordx4 v[164:165], v[160:163], off offset:2048
	global_store_dwordx4 v[164:165], v[156:159], off offset:2064
	s_nop 1
	v_add_co_u32_e32 v156, vcc, 0xb000, v192
	s_nop 1
	v_addc_co_u32_e32 v157, vcc, 0, v193, vcc
	global_store_dwordx4 v[156:157], v[152:155], off
	global_store_dwordx4 v[156:157], v[144:147], off offset:16

.LBB0_1180:
	s_add_u32 s16, s14, 0x100
	s_addc_u32 s17, s15, 0
	s_add_i32 s45, 0, 0x10000
	v_add_u32_e32 v144, s45, v200
	ds_read_b128 v[132:135], v144
	ds_read_b128 v[136:139], v144 offset:1024
	ds_read_b128 v[140:143], v144 offset:2048
	ds_read_b128 v[144:147], v144 offset:3072
	s_cmpk_eq_i32 s44, 0x54
	s_cselect_b32 s21, s1, s17
	s_cselect_b32 s20, s0, s16
	s_cselect_b32 s19, s7, s43
	s_cselect_b32 s18, s6, s42
	s_add_i32 m0, s28, 0xc000
	ds_read_b128 v[148:151], v202
	ds_read_b128 v[152:155], v202 offset:1024
	ds_read_b128 v[156:159], v202 offset:2048
	ds_read_b128 v[160:163], v202 offset:3072
	ds_read_b128 v[164:167], v202 offset:4096
	ds_read_b128 v[168:171], v202 offset:5120
	ds_read_b128 v[172:175], v202 offset:6144
	ds_read_b128 v[186:189], v202 offset:7168
	global_load_lds_dwordx4 v182, s[14:15]
	s_add_i32 m0, s28, 0xe000
	s_nop 0
	global_load_lds_dwordx4 v184, s[14:15]
	s_waitcnt lgkmcnt(8)
	s_setprio 1
	s_barrier
	s_waitcnt lgkmcnt(0)
	v_mfma_f32_16x16x32_bf16 v[128:131], v[132:135], v[148:151], v[128:131]
	v_mfma_f32_16x16x32_bf16 v[128:131], v[136:139], v[152:155], v[128:131]
	v_mfma_f32_16x16x32_bf16 v[112:115], v[136:139], v[160:163], v[112:115]
	v_mfma_f32_16x16x32_bf16 v[112:115], v[132:135], v[156:159], v[112:115]
	v_mfma_f32_16x16x32_bf16 v[96:99], v[132:135], v[164:167], v[96:99]
	v_mfma_f32_16x16x32_bf16 v[96:99], v[136:139], v[168:171], v[96:99]
	v_mfma_f32_16x16x32_bf16 v[80:83], v[136:139], v[186:189], v[80:83]
	v_mfma_f32_16x16x32_bf16 v[80:83], v[132:135], v[172:175], v[80:83]
	v_mfma_f32_16x16x32_bf16 v[76:79], v[140:143], v[172:175], v[76:79]
	v_mfma_f32_16x16x32_bf16 v[76:79], v[144:147], v[186:189], v[76:79]
	v_mfma_f32_16x16x32_bf16 v[92:95], v[144:147], v[168:171], v[92:95]
	v_mfma_f32_16x16x32_bf16 v[92:95], v[140:143], v[164:167], v[92:95]
	v_mfma_f32_16x16x32_bf16 v[108:111], v[140:143], v[156:159], v[108:111]
	v_mfma_f32_16x16x32_bf16 v[108:111], v[144:147], v[160:163], v[108:111]
	v_mfma_f32_16x16x32_bf16 v[124:127], v[144:147], v[152:155], v[124:127]
	v_mfma_f32_16x16x32_bf16 v[124:127], v[140:143], v[148:151], v[124:127]
	s_barrier
	s_setprio 0
	s_add_i32 s46, 0, 0x14000
	s_add_i32 s14, s45, s27
	v_add_u32_e32 v203, s46, v200
	v_lshl_add_u64 v[212:213], s[18:19], 0, v[2:3]
	s_mov_b32 m0, s14
	ds_read_b128 v[190:193], v203
	ds_read_b128 v[194:197], v203 offset:1024
	ds_read_b128 v[204:207], v203 offset:2048
	ds_read_b128 v[208:211], v203 offset:3072
	global_load_lds_dwordx4 v[212:213], off
	v_lshl_add_u64 v[214:215], s[18:19], 0, v[176:177]
	s_add_i32 m0, s14, 0x2000
	s_nop 0
	global_load_lds_dwordx4 v[214:215], off
	s_setprio 1
	s_barrier
	s_waitcnt lgkmcnt(0)
	v_mfma_f32_16x16x32_bf16 v[120:123], v[190:193], v[148:151], v[120:123]
	v_mfma_f32_16x16x32_bf16 v[120:123], v[194:197], v[152:155], v[120:123]
	v_mfma_f32_16x16x32_bf16 v[104:107], v[194:197], v[160:163], v[104:107]
	v_mfma_f32_16x16x32_bf16 v[104:107], v[190:193], v[156:159], v[104:107]
	v_mfma_f32_16x16x32_bf16 v[88:91], v[190:193], v[164:167], v[88:91]
	v_mfma_f32_16x16x32_bf16 v[88:91], v[194:197], v[168:171], v[88:91]
	v_mfma_f32_16x16x32_bf16 v[72:75], v[194:197], v[186:189], v[72:75]
	v_mfma_f32_16x16x32_bf16 v[72:75], v[190:193], v[172:175], v[72:75]
	v_mfma_f32_16x16x32_bf16 v[68:71], v[204:207], v[172:175], v[68:71]
	v_mfma_f32_16x16x32_bf16 v[68:71], v[208:211], v[186:189], v[68:71]
	v_mfma_f32_16x16x32_bf16 v[84:87], v[208:211], v[168:171], v[84:87]
	v_mfma_f32_16x16x32_bf16 v[84:87], v[204:207], v[164:167], v[84:87]
	v_mfma_f32_16x16x32_bf16 v[100:103], v[204:207], v[156:159], v[100:103]
	v_mfma_f32_16x16x32_bf16 v[100:103], v[208:211], v[160:163], v[100:103]
	v_mfma_f32_16x16x32_bf16 v[116:119], v[208:211], v[152:155], v[116:119]
	v_mfma_f32_16x16x32_bf16 v[116:119], v[204:207], v[148:151], v[116:119]
	s_barrier
	s_setprio 0
	s_mov_b32 m0, s28
	v_lshl_add_u64 v[216:217], s[20:21], 0, v[180:181]
	ds_read_b128 v[148:151], v202 offset:16384
	ds_read_b128 v[152:155], v202 offset:17408
	ds_read_b128 v[156:159], v202 offset:18432
	ds_read_b128 v[160:163], v202 offset:19456
	ds_read_b128 v[164:167], v202 offset:20480
	ds_read_b128 v[168:171], v202 offset:21504
	ds_read_b128 v[172:175], v202 offset:22528
	ds_read_b128 v[186:189], v202 offset:23552
	global_load_lds_dwordx4 v[216:217], off
	v_lshl_add_u64 v[218:219], s[20:21], 0, v[178:179]
	s_mov_b32 m0, s29
	s_nop 0
	global_load_lds_dwordx4 v[218:219], off
	s_waitcnt vmcnt(10)
	s_setprio 1
	s_barrier
	s_waitcnt lgkmcnt(0)
	v_mfma_f32_16x16x32_bf16 v[64:67], v[132:135], v[148:151], v[64:67]
	v_mfma_f32_16x16x32_bf16 v[64:67], v[136:139], v[152:155], v[64:67]
	v_mfma_f32_16x16x32_bf16 v[48:51], v[136:139], v[160:163], v[48:51]
	v_mfma_f32_16x16x32_bf16 v[48:51], v[132:135], v[156:159], v[48:51]
	v_mfma_f32_16x16x32_bf16 v[32:35], v[132:135], v[164:167], v[32:35]
	v_mfma_f32_16x16x32_bf16 v[32:35], v[136:139], v[168:171], v[32:35]
	v_mfma_f32_16x16x32_bf16 v[16:19], v[136:139], v[186:189], v[16:19]
	v_mfma_f32_16x16x32_bf16 v[16:19], v[132:135], v[172:175], v[16:19]
	v_mfma_f32_16x16x32_bf16 v[12:15], v[140:143], v[172:175], v[12:15]
	v_mfma_f32_16x16x32_bf16 v[12:15], v[144:147], v[186:189], v[12:15]
	v_mfma_f32_16x16x32_bf16 v[28:31], v[144:147], v[168:171], v[28:31]
	v_mfma_f32_16x16x32_bf16 v[28:31], v[140:143], v[164:167], v[28:31]
	v_mfma_f32_16x16x32_bf16 v[44:47], v[140:143], v[156:159], v[44:47]
	v_mfma_f32_16x16x32_bf16 v[44:47], v[144:147], v[160:163], v[44:47]
	v_mfma_f32_16x16x32_bf16 v[60:63], v[144:147], v[152:155], v[60:63]
	v_mfma_f32_16x16x32_bf16 v[60:63], v[140:143], v[148:151], v[60:63]
	s_barrier
	s_setprio 0
	s_add_u32 s14, s18, 0x160000
	s_addc_u32 s15, s19, 0
	s_add_i32 s45, s46, s27
	v_lshl_add_u64 v[132:133], s[14:15], 0, v[2:3]
	s_mov_b32 m0, s45
	s_nop 0
	global_load_lds_dwordx4 v[132:133], off
	v_lshl_add_u64 v[132:133], s[14:15], 0, v[176:177]
	s_add_i32 m0, s45, 0x2000
	s_nop 0
	global_load_lds_dwordx4 v[132:133], off
	s_add_i32 s45, 0, 0x18000
	v_add_u32_e32 v144, s45, v200
	ds_read_b128 v[132:135], v144
	ds_read_b128 v[136:139], v144 offset:1024
	ds_read_b128 v[140:143], v144 offset:2048
	ds_read_b128 v[144:147], v144 offset:3072
	s_waitcnt vmcnt(6)
	s_setprio 1
	s_barrier
	v_mfma_f32_16x16x32_bf16 v[56:59], v[190:193], v[148:151], v[56:59]
	v_mfma_f32_16x16x32_bf16 v[56:59], v[194:197], v[152:155], v[56:59]
	v_mfma_f32_16x16x32_bf16 v[40:43], v[194:197], v[160:163], v[40:43]
	v_mfma_f32_16x16x32_bf16 v[40:43], v[190:193], v[156:159], v[40:43]
	v_mfma_f32_16x16x32_bf16 v[24:27], v[190:193], v[164:167], v[24:27]
	v_mfma_f32_16x16x32_bf16 v[24:27], v[194:197], v[168:171], v[24:27]
	v_mfma_f32_16x16x32_bf16 v[8:11], v[194:197], v[186:189], v[8:11]
	v_mfma_f32_16x16x32_bf16 v[8:11], v[190:193], v[172:175], v[8:11]
	v_mfma_f32_16x16x32_bf16 v[4:7], v[204:207], v[172:175], v[4:7]
	v_mfma_f32_16x16x32_bf16 v[4:7], v[208:211], v[186:189], v[4:7]
	v_mfma_f32_16x16x32_bf16 v[20:23], v[208:211], v[168:171], v[20:23]
	v_mfma_f32_16x16x32_bf16 v[20:23], v[204:207], v[164:167], v[20:23]
	v_mfma_f32_16x16x32_bf16 v[36:39], v[204:207], v[156:159], v[36:39]
	v_mfma_f32_16x16x32_bf16 v[36:39], v[208:211], v[160:163], v[36:39]
	v_mfma_f32_16x16x32_bf16 v[52:55], v[208:211], v[152:155], v[52:55]
	v_mfma_f32_16x16x32_bf16 v[52:55], v[204:207], v[148:151], v[52:55]
	s_barrier
	s_setprio 0
	s_add_u32 s14, s20, 0x160000
	s_addc_u32 s15, s21, 0
	s_mov_b32 m0, s30
	ds_read_b128 v[148:151], v202 offset:32768
	ds_read_b128 v[152:155], v202 offset:33792
	ds_read_b128 v[156:159], v202 offset:34816
	ds_read_b128 v[160:163], v202 offset:35840
	ds_read_b128 v[164:167], v202 offset:36864
	ds_read_b128 v[168:171], v202 offset:37888
	ds_read_b128 v[172:175], v202 offset:38912
	ds_read_b128 v[186:189], v202 offset:39936
	global_load_lds_dwordx4 v180, s[14:15]
	s_mov_b32 m0, s31
	s_nop 0
	global_load_lds_dwordx4 v178, s[14:15]
	s_waitcnt lgkmcnt(8)
	s_setprio 1
	s_barrier
	s_waitcnt lgkmcnt(0)
	v_mfma_f32_16x16x32_bf16 v[128:131], v[132:135], v[148:151], v[128:131]
	v_mfma_f32_16x16x32_bf16 v[128:131], v[136:139], v[152:155], v[128:131]
	v_mfma_f32_16x16x32_bf16 v[112:115], v[136:139], v[160:163], v[112:115]
	v_mfma_f32_16x16x32_bf16 v[112:115], v[132:135], v[156:159], v[112:115]
	v_mfma_f32_16x16x32_bf16 v[96:99], v[132:135], v[164:167], v[96:99]
	v_mfma_f32_16x16x32_bf16 v[96:99], v[136:139], v[168:171], v[96:99]
	v_mfma_f32_16x16x32_bf16 v[80:83], v[136:139], v[186:189], v[80:83]
	v_mfma_f32_16x16x32_bf16 v[80:83], v[132:135], v[172:175], v[80:83]
	v_mfma_f32_16x16x32_bf16 v[76:79], v[140:143], v[172:175], v[76:79]
	v_mfma_f32_16x16x32_bf16 v[76:79], v[144:147], v[186:189], v[76:79]
	v_mfma_f32_16x16x32_bf16 v[92:95], v[144:147], v[168:171], v[92:95]
	v_mfma_f32_16x16x32_bf16 v[92:95], v[140:143], v[164:167], v[92:95]
	v_mfma_f32_16x16x32_bf16 v[108:111], v[140:143], v[156:159], v[108:111]
	v_mfma_f32_16x16x32_bf16 v[108:111], v[144:147], v[160:163], v[108:111]
	v_mfma_f32_16x16x32_bf16 v[124:127], v[144:147], v[152:155], v[124:127]
	v_mfma_f32_16x16x32_bf16 v[124:127], v[140:143], v[148:151], v[124:127]
	s_barrier
	s_setprio 0
	s_add_i32 s20, 0, 0x1c000
	s_add_i32 s14, s45, s27
	v_add_u32_e32 v203, s20, v200
	v_lshl_add_u64 v[212:213], v[212:213], 0, s[2:3]
	s_mov_b32 m0, s14
	ds_read_b128 v[190:193], v203
	ds_read_b128 v[194:197], v203 offset:1024
	ds_read_b128 v[204:207], v203 offset:2048
	ds_read_b128 v[208:211], v203 offset:3072
	global_load_lds_dwordx4 v[212:213], off
	v_lshl_add_u64 v[212:213], v[214:215], 0, s[2:3]
	s_add_i32 m0, s14, 0x2000
	s_nop 0
	global_load_lds_dwordx4 v[212:213], off
	s_setprio 1
	s_barrier
	s_waitcnt lgkmcnt(0)
	v_mfma_f32_16x16x32_bf16 v[120:123], v[190:193], v[148:151], v[120:123]
	v_mfma_f32_16x16x32_bf16 v[120:123], v[194:197], v[152:155], v[120:123]
	v_mfma_f32_16x16x32_bf16 v[104:107], v[194:197], v[160:163], v[104:107]
	v_mfma_f32_16x16x32_bf16 v[104:107], v[190:193], v[156:159], v[104:107]
	v_mfma_f32_16x16x32_bf16 v[88:91], v[190:193], v[164:167], v[88:91]
	v_mfma_f32_16x16x32_bf16 v[88:91], v[194:197], v[168:171], v[88:91]
	v_mfma_f32_16x16x32_bf16 v[72:75], v[194:197], v[186:189], v[72:75]
	v_mfma_f32_16x16x32_bf16 v[72:75], v[190:193], v[172:175], v[72:75]
	v_mfma_f32_16x16x32_bf16 v[68:71], v[204:207], v[172:175], v[68:71]
	v_mfma_f32_16x16x32_bf16 v[68:71], v[208:211], v[186:189], v[68:71]
	v_mfma_f32_16x16x32_bf16 v[84:87], v[208:211], v[168:171], v[84:87]
	v_mfma_f32_16x16x32_bf16 v[84:87], v[204:207], v[164:167], v[84:87]
	v_mfma_f32_16x16x32_bf16 v[100:103], v[204:207], v[156:159], v[100:103]
	v_mfma_f32_16x16x32_bf16 v[100:103], v[208:211], v[160:163], v[100:103]
	v_mfma_f32_16x16x32_bf16 v[116:119], v[208:211], v[152:155], v[116:119]
	v_mfma_f32_16x16x32_bf16 v[116:119], v[204:207], v[148:151], v[116:119]
	s_barrier
	s_setprio 0
	s_mov_b32 m0, s36
	v_lshl_add_u64 v[212:213], v[216:217], 0, s[2:3]
	ds_read_b128 v[148:151], v202 offset:49152
	ds_read_b128 v[152:155], v202 offset:50176
	ds_read_b128 v[156:159], v202 offset:51200
	ds_read_b128 v[160:163], v202 offset:52224
	ds_read_b128 v[164:167], v202 offset:53248
	ds_read_b128 v[168:171], v202 offset:54272
	ds_read_b128 v[172:175], v202 offset:55296
	ds_read_b128 v[186:189], v202 offset:56320
	global_load_lds_dwordx4 v[212:213], off
	v_lshl_add_u64 v[212:213], v[218:219], 0, s[2:3]
	s_mov_b32 m0, s37
	s_nop 0
	global_load_lds_dwordx4 v[212:213], off
	s_setprio 1
	s_barrier
	s_waitcnt lgkmcnt(0)
	v_mfma_f32_16x16x32_bf16 v[64:67], v[132:135], v[148:151], v[64:67]
	v_mfma_f32_16x16x32_bf16 v[64:67], v[136:139], v[152:155], v[64:67]
	v_mfma_f32_16x16x32_bf16 v[48:51], v[136:139], v[160:163], v[48:51]
	v_mfma_f32_16x16x32_bf16 v[48:51], v[132:135], v[156:159], v[48:51]
	v_mfma_f32_16x16x32_bf16 v[32:35], v[132:135], v[164:167], v[32:35]
	v_mfma_f32_16x16x32_bf16 v[32:35], v[136:139], v[168:171], v[32:35]
	v_mfma_f32_16x16x32_bf16 v[16:19], v[136:139], v[186:189], v[16:19]
	v_mfma_f32_16x16x32_bf16 v[16:19], v[132:135], v[172:175], v[16:19]
	v_mfma_f32_16x16x32_bf16 v[12:15], v[140:143], v[172:175], v[12:15]
	v_mfma_f32_16x16x32_bf16 v[12:15], v[144:147], v[186:189], v[12:15]
	v_mfma_f32_16x16x32_bf16 v[28:31], v[144:147], v[168:171], v[28:31]
	v_mfma_f32_16x16x32_bf16 v[28:31], v[140:143], v[164:167], v[28:31]
	v_mfma_f32_16x16x32_bf16 v[44:47], v[140:143], v[156:159], v[44:47]
	v_mfma_f32_16x16x32_bf16 v[44:47], v[144:147], v[160:163], v[44:47]
	v_mfma_f32_16x16x32_bf16 v[60:63], v[144:147], v[152:155], v[60:63]
	v_mfma_f32_16x16x32_bf16 v[60:63], v[140:143], v[148:151], v[60:63]
	s_barrier
	s_setprio 0
	s_add_u32 s14, s18, 0x160080
	s_addc_u32 s15, s19, 0
	s_add_i32 s18, s20, s27
	v_lshl_add_u64 v[132:133], s[14:15], 0, v[2:3]
	s_mov_b32 m0, s18
	s_nop 0
	global_load_lds_dwordx4 v[132:133], off
	v_lshl_add_u64 v[132:133], s[14:15], 0, v[176:177]
	s_add_i32 m0, s18, 0x2000
	s_nop 0
	global_load_lds_dwordx4 v[132:133], off
	s_waitcnt vmcnt(6)
	s_setprio 1
	s_barrier
	v_mfma_f32_16x16x32_bf16 v[56:59], v[190:193], v[148:151], v[56:59]
	v_mfma_f32_16x16x32_bf16 v[56:59], v[194:197], v[152:155], v[56:59]
	v_mfma_f32_16x16x32_bf16 v[40:43], v[194:197], v[160:163], v[40:43]
	v_mfma_f32_16x16x32_bf16 v[40:43], v[190:193], v[156:159], v[40:43]
	v_mfma_f32_16x16x32_bf16 v[24:27], v[190:193], v[164:167], v[24:27]
	v_mfma_f32_16x16x32_bf16 v[24:27], v[194:197], v[168:171], v[24:27]
	v_mfma_f32_16x16x32_bf16 v[8:11], v[194:197], v[186:189], v[8:11]
	v_mfma_f32_16x16x32_bf16 v[8:11], v[190:193], v[172:175], v[8:11]
	v_mfma_f32_16x16x32_bf16 v[4:7], v[204:207], v[172:175], v[4:7]
	v_mfma_f32_16x16x32_bf16 v[4:7], v[208:211], v[186:189], v[4:7]
	v_mfma_f32_16x16x32_bf16 v[20:23], v[208:211], v[168:171], v[20:23]
	v_mfma_f32_16x16x32_bf16 v[20:23], v[204:207], v[164:167], v[20:23]
	v_mfma_f32_16x16x32_bf16 v[36:39], v[204:207], v[156:159], v[36:39]
	v_mfma_f32_16x16x32_bf16 v[36:39], v[208:211], v[160:163], v[36:39]
	v_mfma_f32_16x16x32_bf16 v[52:55], v[208:211], v[152:155], v[52:55]
	v_mfma_f32_16x16x32_bf16 v[52:55], v[204:207], v[148:151], v[52:55]
	s_barrier
	s_setprio 0
	s_add_i32 s44, s44, 2
	s_add_u32 s42, s42, 0x100
	s_addc_u32 s43, s43, 0
	s_cmpk_gt_u32 s44, 0x55
	s_mov_b64 s[14:15], s[16:17]
	s_cbranch_scc0 .LBB0_1180
	s_cmp_lt_i32 s41, 32
	s_mov_b64 s[14:15], 0
	s_cbranch_scc1 .LBB0_1183
	s_sub_i32 s14, s41, 32
	s_lshr_b32 s14, s14, 4
	s_add_i32 s14, s14, 1
	s_mul_hi_u32 s15, s14, 0x3000
	s_mulk_i32 s14, 0x3000
